# opt20: attention loops: removed 250 redundant v_max(x,x) canonicalisations (hazard distances re-checked, 5 sites padded)
# speedup vs baseline: 1.0088x; 1.0032x over previous
; #define MFMA16(a, b, c) __builtin_amdgcn_mfma_f32_16x16x32_f16((a), (b), (c), 0, 0, 0)
; __device__ __forceinline__ float shx(float v, int m) { return __shfl_xor(v, m); }
;     ...
;         for (int s_ = 0; s_ < NS; ++s_) {
;             f32x4 s[4];
; #pragma unroll
;             for (int t = 0; t < 4; ++t) { s[t] = MFMA16(ka[2 * t], qf[s_][0], z); s[t] = MFMA16(ka[2 * t + 1], qf[s_][1], s[t]); }
;             if (s_ == NS - 1) {
;                 const half_t* kpA = kf + (size_t)nbA * 2048; const half_t* kpB = kf + (size_t)nbB * 2048;
; #pragma unroll
;                 for (int i = 0; i < 4; ++i) { ka[i] = *(const half8*)(kpA + i * 512); ka[4 + i] = *(const half8*)(kpB + i * 512); }
;             }
;             if (MODE != 1) {
;                 float mx = -1e30f;
; #pragma unroll
;                 for (int t = 0; t < 4; ++t)
; #pragma unroll
;                     for (int r = 0; r < 4; ++r) { if (valid(s_, kbA + 16 * t + 4 * g + r)) mx = fmaxf(mx, s[t][r]); }
;                 if (__ballot(mx > m[s_] + RESC_THR) != 0ull) {
;                     mx = fmaxf(mx, shx(mx, 16)); mx = fmaxf(mx, shx(mx, 32));
;                     const float mn = fmaxf(m[s_], mx); const float corr = __builtin_amdgcn_exp2f(m[s_] - mn); m[s_] = mn; l[s_] = l[s_] * corr;
;                     if (PV) {
; #pragma unroll
;                         for (int dt = 0; dt < 4; ++dt) o[s_][dt] = o[s_][dt] * corr;
;                     }
;                 }
;             }
.LBB0_694:
	s_waitcnt vmcnt(0) lgkmcnt(0)
	v_mfma_f32_16x16x32_f16 v[50:53], v[18:21], v[2:5], 0
	v_or_b32_e32 v91, s33, v166
	v_cmp_gt_i32_e64 s[10:11], v91, v122
	v_cmp_lt_i32_e64 s[12:13], v91, v122
	v_mfma_f32_16x16x32_f16 v[54:57], v[42:45], v[6:9], v[50:53]
	v_or_b32_e32 v97, 2, v91
	v_cmp_gt_i32_e64 s[14:15], v97, v122
	v_or_b32_e32 v100, 3, v91
	v_cmp_gt_i32_e64 s[16:17], v100, v122
	v_or_b32_e32 v101, 16, v91
	s_nop 2
	v_max_f32_e32 v50, 0xf149f2ca, v54
	v_cndmask_b32_e64 v59, v50, v172, s[10:11]
	v_mfma_f32_16x16x32_f16 v[50:53], v[46:49], v[2:5], 0
	v_max_f32_e32 v58, v59, v55
	v_cndmask_b32_e64 v62, v59, v58, s[12:13]
	v_mfma_f32_16x16x32_f16 v[58:61], v[38:41], v[6:9], v[50:53]
	v_max_f32_e32 v67, v57, v57
	v_cmp_gt_i32_e64 s[18:19], v101, v122
	v_or_b32_e32 v102, 17, v91
	s_nop 0
	s_nop 0
	v_max_f32_e32 v50, v56, v56
	v_max_f32_e32 v63, v62, v50
	v_mfma_f32_16x16x32_f16 v[50:53], v[22:25], v[2:5], 0
	v_cndmask_b32_e64 v66, v63, v62, s[14:15]
	v_max_f32_e32 v68, v59, v59
	v_cmp_gt_i32_e64 s[22:23], v102, v122
	v_mfma_f32_16x16x32_f16 v[62:65], v[26:29], v[6:9], v[50:53]
	v_or_b32_e32 v99, 18, v91
	v_cmp_gt_i32_e64 s[20:21], v99, v122
	v_or_b32_e32 v98, 19, v91
	s_nop 0
	v_max_f32_e32 v50, v66, v67
	v_cndmask_b32_e64 v66, v50, v66, s[16:17]
	v_max_f32_e32 v67, v66, v58
	v_cndmask_b32_e64 v66, v67, v66, s[18:19]
	v_max_f32_e32 v67, v66, v68
	v_cndmask_b32_e64 v66, v67, v66, s[22:23]
	v_max_f32_e32 v68, v60, v60
	v_max_f32_e32 v67, v66, v68
	v_cndmask_b32_e64 v66, v67, v66, s[20:21]
	v_max_f32_e32 v68, v61, v61
	v_max_f32_e32 v67, v66, v68
	v_cmp_gt_i32_e64 s[26:27], v98, v122
	v_or_b32_e32 v96, 32, v91
	v_max_f32_e32 v68, v62, v62
	v_cndmask_b32_e64 v66, v67, v66, s[26:27]
	v_max_f32_e32 v67, v66, v68
	v_cmp_gt_i32_e64 s[24:25], v96, v122
	v_or_b32_e32 v95, 33, v91
	v_max_f32_e32 v68, v63, v63
	v_cndmask_b32_e64 v66, v67, v66, s[24:25]
	v_mfma_f32_16x16x32_f16 v[50:53], v[30:33], v[2:5], 0
	v_max_f32_e32 v67, v66, v68
	v_cmp_gt_i32_e64 s[30:31], v95, v122
	v_or_b32_e32 v94, 34, v91
	v_max_f32_e32 v68, v64, v64
	v_cndmask_b32_e64 v66, v67, v66, s[30:31]
	v_max_f32_e32 v67, v66, v68
	v_cmp_gt_i32_e64 s[28:29], v94, v122
	v_mfma_f32_16x16x32_f16 v[50:53], v[34:37], v[6:9], v[50:53]
	v_or_b32_e32 v93, 35, v91
	v_cndmask_b32_e64 v66, v67, v66, s[28:29]
	v_max_f32_e32 v68, v65, v65
	v_max_f32_e32 v67, v66, v68
	v_cmp_gt_i32_e64 s[36:37], v93, v122
	v_or_b32_e32 v92, 48, v91
	s_nop 0
	s_nop 0
	v_max_f32_e32 v68, v50, v50
	v_cndmask_b32_e64 v66, v67, v66, s[36:37]
	v_max_f32_e32 v67, v66, v68
	v_cmp_gt_i32_e64 s[34:35], v92, v122
	v_or_b32_e32 v90, 49, v91
	v_max_f32_e32 v68, v51, v51
	v_cndmask_b32_e64 v66, v67, v66, s[34:35]
	v_max_f32_e32 v67, v66, v68
	v_cmp_gt_i32_e64 s[40:41], v90, v122
	v_or_b32_e32 v89, 50, v91
	v_max_f32_e32 v68, v52, v52
	v_cndmask_b32_e64 v66, v67, v66, s[40:41]
	v_max_f32_e32 v67, v66, v68
	v_cmp_gt_i32_e64 s[38:39], v89, v122
	v_or_b32_e32 v88, 51, v91
	v_max_f32_e32 v68, v53, v53
	v_cndmask_b32_e64 v66, v67, v66, s[38:39]
	v_max_f32_e32 v67, v66, v68
	v_cmp_gt_i32_e64 s[42:43], v88, v122
	s_nop 1
	v_cndmask_b32_e64 v66, v67, v66, s[42:43]
	v_add_f32_e32 v67, 0x41400000, v128
	v_cmp_gt_f32_e32 vcc, v66, v67
	s_cbranch_vccz .LBB0_696
	v_and_b32_e32 v68, 64, v204
	v_xor_b32_e32 v67, 16, v204
	v_add_u32_e32 v68, 64, v68
	v_cmp_lt_i32_e32 vcc, v67, v68
	v_mov_b32_e32 v85, v129
	s_nop 0
	v_cndmask_b32_e32 v67, v204, v67, vcc
	v_lshlrev_b32_e32 v67, 2, v67
	ds_bpermute_b32 v67, v67, v66
	v_max_f32_e32 v66, v66, v66
	s_waitcnt lgkmcnt(0)
	v_max_f32_e32 v67, v67, v67
	v_max_f32_e32 v66, v66, v67
	v_xor_b32_e32 v67, 32, v204
	v_cmp_lt_i32_e32 vcc, v67, v68
	s_nop 1
	v_cndmask_b32_e32 v67, v204, v67, vcc
	v_lshlrev_b32_e32 v67, 2, v67
	ds_bpermute_b32 v67, v67, v66
	s_waitcnt lgkmcnt(0)
	v_max3_f32 v84, v128, v66, v67
	v_sub_f32_e32 v66, v128, v84
	v_exp_f32_e32 v66, v66
	v_mov_b64_e32 v[128:129], v[84:85]
	v_mul_f32_e32 v82, v82, v66
	s_branch .LBB0_697

; #define MFMA16(a, b, c) __builtin_amdgcn_mfma_f32_16x16x32_f16((a), (b), (c), 0, 0, 0)
; __device__ __forceinline__ float shx(float v, int m) { return __shfl_xor(v, m); }
;     ...
;     for (int it = 0; it < nit; ++it) {
;         const int kbN = kbof((it + 1 < nit) ? it + 1 : it);
;         const int nbA = kbN >> 5, nbB = (nbA + 1 <= maxblk) ? nbA + 1 : maxblk;
;         const f32x4 z = {0.f, 0.f, 0.f, 0.f};
; #pragma unroll
;         for (int s_ = 0; s_ < NS; ++s_) {
;             f32x4 s[4];
; #pragma unroll
;             for (int t = 0; t < 4; ++t) { s[t] = MFMA16(ka[2 * t], qf[s_][0], z); s[t] = MFMA16(ka[2 * t + 1], qf[s_][1], s[t]); }
;             if (s_ == NS - 1) {
;                 const half_t* kpA = kf + (size_t)nbA * 2048; const half_t* kpB = kf + (size_t)nbB * 2048;
; #pragma unroll
;                 for (int i = 0; i < 4; ++i) { ka[i] = *(const half8*)(kpA + i * 512); ka[4 + i] = *(const half8*)(kpB + i * 512); }
;             }
;             if (MODE != 1) {
;                 float mx = -1e30f;
; #pragma unroll
;                 for (int t = 0; t < 4; ++t)
; #pragma unroll
;                     for (int r = 0; r < 4; ++r) { if (valid(s_, kbA + 16 * t + 4 * g + r)) mx = fmaxf(mx, s[t][r]); }
;                 if (__ballot(mx > m[s_] + RESC_THR) != 0ull) {
;                     mx = fmaxf(mx, shx(mx, 16)); mx = fmaxf(mx, shx(mx, 32));
;                     const float mn = fmaxf(m[s_], mx); const float corr = __builtin_amdgcn_exp2f(m[s_] - mn); m[s_] = mn; l[s_] = l[s_] * corr;
;                     if (PV) {
; #pragma unroll
;                         for (int dt = 0; dt < 4; ++dt) o[s_][dt] = o[s_][dt] * corr;
;                     }
;                 }
;             }
.LBB0_697:
	v_mfma_f32_16x16x32_f16 v[18:21], v[18:21], v[10:13], 0
	s_add_i32 s94, s44, 1
	s_cmp_lt_u32 s94, s88
	s_cselect_b32 s33, s94, s44
	v_mfma_f32_16x16x32_f16 v[78:81], v[42:45], v[14:17], v[18:21]
	s_lshl_b32 s33, s33, 6
	s_lshr_b32 s84, s33, 5
	s_min_u32 s46, s84, 30
	v_mfma_f32_16x16x32_f16 v[18:21], v[46:49], v[10:13], 0
	s_lshl_b64 s[44:45], s[84:85], 12
	s_lshl_b32 s84, s46, 12
	v_lshl_add_u64 v[104:105], v[126:127], 0, s[44:45]
	v_mfma_f32_16x16x32_f16 v[74:77], v[38:41], v[14:17], v[18:21]
	v_lshl_add_u64 v[106:107], v[126:127], 0, s[84:85]
	s_movk_i32 s44, 0x1000
	v_mfma_f32_16x16x32_f16 v[18:21], v[22:25], v[10:13], 0
	v_max_f32_e32 v85, 0xf149f2ca, v78
	v_cmp_lt_i32_e64 s[46:47], v91, v124
	v_cmp_gt_i32_e64 s[48:49], v97, v124
	v_mfma_f32_16x16x32_f16 v[70:73], v[26:29], v[14:17], v[18:21]
	v_cmp_gt_i32_e64 s[50:51], v100, v124
	v_cmp_gt_i32_e64 s[52:53], v101, v124
	v_max_f32_e32 v97, v75, v75
	v_mfma_f32_16x16x32_f16 v[18:21], v[30:33], v[10:13], 0
	v_cmp_gt_i32_e64 s[54:55], v102, v124
	v_cmp_gt_i32_e64 s[56:57], v99, v124
	v_cmp_gt_i32_e64 s[58:59], v98, v124
	v_mfma_f32_16x16x32_f16 v[66:69], v[34:37], v[14:17], v[18:21]
	v_add_co_u32_e32 v34, vcc, s44, v106
	v_cmp_gt_i32_e64 s[44:45], v91, v124
	s_nop 0
	v_addc_co_u32_e32 v35, vcc, 0, v107, vcc
	flat_load_dwordx4 v[18:21], v[104:105]
	flat_load_dwordx4 v[22:25], v[34:35]
	flat_load_dwordx4 v[42:45], v[104:105] offset:1024
	flat_load_dwordx4 v[26:29], v[34:35] offset:1024
	flat_load_dwordx4 v[46:49], v[104:105] offset:2048
	flat_load_dwordx4 v[30:33], v[34:35] offset:2048
	flat_load_dwordx4 v[38:41], v[104:105] offset:3072
	s_nop 0
	flat_load_dwordx4 v[34:37], v[34:35] offset:3072
	v_cndmask_b32_e64 v85, v85, v172, s[44:45]
	v_max_f32_e32 v91, v85, v79
	v_cndmask_b32_e64 v85, v85, v91, s[46:47]
	v_max_f32_e32 v91, v85, v80
	v_cndmask_b32_e64 v85, v91, v85, s[48:49]
	v_max_f32_e32 v91, v85, v81
	v_cndmask_b32_e64 v85, v91, v85, s[50:51]
	v_max_f32_e32 v91, v85, v74
	v_cndmask_b32_e64 v85, v91, v85, s[52:53]
	v_max_f32_e32 v91, v85, v97
	v_cndmask_b32_e64 v85, v91, v85, s[54:55]
	v_max_f32_e32 v97, v76, v76
	v_max_f32_e32 v91, v85, v97
	v_cndmask_b32_e64 v85, v91, v85, s[56:57]
	v_max_f32_e32 v97, v77, v77
	v_max_f32_e32 v91, v85, v97
	v_cndmask_b32_e64 v85, v91, v85, s[58:59]
	v_cmp_gt_i32_e64 s[60:61], v96, v124
	v_max_f32_e32 v96, v70, v70
	v_max_f32_e32 v91, v85, v96
	v_cndmask_b32_e64 v85, v91, v85, s[60:61]
	v_cmp_gt_i32_e64 s[62:63], v95, v124
	v_max_f32_e32 v95, v71, v71
	v_max_f32_e32 v91, v85, v95
	v_cndmask_b32_e64 v85, v91, v85, s[62:63]
	v_cmp_gt_i32_e64 s[64:65], v94, v124
	v_max_f32_e32 v94, v72, v72
	v_max_f32_e32 v91, v85, v94
	v_cndmask_b32_e64 v85, v91, v85, s[64:65]
	v_cmp_gt_i32_e64 s[66:67], v93, v124
	v_max_f32_e32 v93, v73, v73
	v_max_f32_e32 v91, v85, v93
	v_cndmask_b32_e64 v85, v91, v85, s[66:67]
	v_cmp_gt_i32_e64 s[68:69], v92, v124
	v_max_f32_e32 v92, v66, v66
	v_max_f32_e32 v91, v85, v92
	v_cndmask_b32_e64 v85, v91, v85, s[68:69]
	v_cmp_gt_i32_e64 s[70:71], v90, v124
	v_max_f32_e32 v91, v67, v67
	v_max_f32_e32 v90, v85, v91
	v_cndmask_b32_e64 v85, v90, v85, s[70:71]
	v_cmp_gt_i32_e64 s[72:73], v89, v124
	v_max_f32_e32 v90, v68, v68
	v_max_f32_e32 v89, v85, v90
	v_cndmask_b32_e64 v85, v89, v85, s[72:73]
	v_cmp_gt_i32_e64 s[74:75], v88, v124
	v_max_f32_e32 v89, v69, v69
	v_max_f32_e32 v88, v85, v89
	v_cndmask_b32_e64 v85, v88, v85, s[74:75]
	v_add_f32_e32 v88, 0x41400000, v129
	v_cmp_gt_f32_e32 vcc, v85, v88
	s_cbranch_vccz .LBB0_699
	v_and_b32_e32 v89, 64, v204
	v_xor_b32_e32 v88, 16, v204
	v_add_u32_e32 v89, 64, v89
	v_cmp_lt_i32_e32 vcc, v88, v89
	s_nop 1
	v_cndmask_b32_e32 v88, v204, v88, vcc
	v_lshlrev_b32_e32 v88, 2, v88
	ds_bpermute_b32 v88, v88, v85
	v_max_f32_e32 v85, v85, v85
	s_waitcnt lgkmcnt(0)
	v_max_f32_e32 v88, v88, v88
	v_max_f32_e32 v85, v85, v88
	v_xor_b32_e32 v88, 32, v204
	v_cmp_lt_i32_e32 vcc, v88, v89
	s_nop 1
	v_cndmask_b32_e32 v88, v204, v88, vcc
	v_lshlrev_b32_e32 v88, 2, v88
	ds_bpermute_b32 v88, v88, v85
	s_waitcnt lgkmcnt(0)
	v_max3_f32 v85, v129, v85, v88
	v_sub_f32_e32 v88, v129, v85
	v_exp_f32_e32 v88, v88
	v_mov_b32_e32 v129, v85
	v_mul_f32_e32 v83, v83, v88
	s_branch .LBB0_700

; template <class KB>
; __device__ __forceinline__ void sel_run(int nit, KB kbof, const half8 (&qf)[2][2], const unsigned char* kf, const unsigned char* vf, const int (&tqs)[2], int qq,
;                                         f32x4 (&o)[2][4], float (&m)[2], float (&l)[2], int g) {
;     ...
;     for (int it = 0; it < nit; ++it) {
;         const int eN = kbof((it + 1 < nit) ? it + 1 : it);
;         const int kbN = 64 * (eN & 255);
;         const unsigned maskA = (unsigned)eA >> 8;
;         bool selq[2], need[2];
; #pragma unroll
;         for (int s_ = 0; s_ < 2; ++s_) { selq[s_] = ((maskA >> (4 * s_ + qq)) & 1u) != 0u; need[s_] = ((maskA >> (4 * s_)) & 15u) != 0u; }
;         half8 kh[8];
; #pragma unroll
;         for (int i = 0; i < 8; ++i) kh[i] = fp8x8_to_half8(ka[i]);
;         {
;             const unsigned char* kp = kf + (size_t)(kbN >> 5) * 2048;
; #pragma unroll
;             for (int i = 0; i < 8; ++i) ka[i] = *(const u32x2*)(kp + i * 512);
;         }
;         const f32x4 z = {0.f, 0.f, 0.f, 0.f};
;         f32x4 s[2][4];
; #pragma unroll
;         for (int s_ = 0; s_ < 2; ++s_)
;             if (need[s_]) {
; #pragma unroll
;                 for (int t = 0; t < 4; ++t) { s[s_][t] = MFMA16(kh[2 * t], qf[s_][0], z); s[s_][t] = MFMA16(kh[2 * t + 1], qf[s_][1], s[s_][t]); }
;             }
;         half8 vh[8];
; #pragma unroll
;         for (int i = 0; i < 8; ++i) vh[i] = fp8x8_to_half8(va[i]);
;         {
;             const unsigned char* vp = vf + (size_t)(kbN >> 5) * 2048;
; #pragma unroll
;             for (int i = 0; i < 8; ++i) va[i] = *(const u32x2*)(vp + i * 512);
;         }
; #pragma unroll
;         for (int s_ = 0; s_ < 2; ++s_)
;             if (need[s_]) {
;                 float p[4][4]; float mx = -1e30f;
;                 const int klim = selq[s_] ? tqs[s_] - kbA - 4 * g : -1;
; #pragma unroll
;                 for (int t = 0; t < 4; ++t)
; #pragma unroll
;                     for (int r = 0; r < 4; ++r) { if (16 * t + r <= klim) mx = fmaxf(mx, s[s_][t][r]); }
;                 if (__ballot(mx > m[s_] + RESC_THR) != 0ull) {
;                     mx = fmaxf(mx, shx(mx, 16)); mx = fmaxf(mx, shx(mx, 32));
;                     const float mn = fmaxf(m[s_], mx); const float corr = __builtin_amdgcn_exp2f(m[s_] - mn); m[s_] = mn;
;                     l[s_] = l[s_] * corr;
; #pragma unroll
.LBB0_934:
	s_waitcnt vmcnt(8)
	v_cvt_scalef32_pk_f16_fp8 v90, v122, 1.0
	v_cvt_scalef32_pk_f16_fp8 v91, v122, 1.0 op_sel:[1,0,0]
	v_cvt_scalef32_pk_f16_fp8 v92, v123, 1.0
	v_cvt_scalef32_pk_f16_fp8 v93, v123, 1.0 op_sel:[1,0,0]
	v_lshl_add_u64 v[122:123], v[120:121], 0, s[84:85]
	v_cvt_scalef32_pk_f16_fp8 v102, v188, 1.0
	v_cvt_scalef32_pk_f16_fp8 v103, v188, 1.0 op_sel:[1,0,0]
	v_cvt_scalef32_pk_f16_fp8 v104, v189, 1.0
	v_cvt_scalef32_pk_f16_fp8 v105, v189, 1.0 op_sel:[1,0,0]
	v_cvt_scalef32_pk_f16_fp8 v94, v186, 1.0
	v_cvt_scalef32_pk_f16_fp8 v95, v186, 1.0 op_sel:[1,0,0]
	v_cvt_scalef32_pk_f16_fp8 v96, v187, 1.0
	v_cvt_scalef32_pk_f16_fp8 v97, v187, 1.0 op_sel:[1,0,0]
	v_cvt_scalef32_pk_f16_fp8 v86, v184, 1.0
	v_cvt_scalef32_pk_f16_fp8 v87, v184, 1.0 op_sel:[1,0,0]
	v_cvt_scalef32_pk_f16_fp8 v88, v185, 1.0
	v_cvt_scalef32_pk_f16_fp8 v89, v185, 1.0 op_sel:[1,0,0]
	v_cvt_scalef32_pk_f16_fp8 v82, v180, 1.0
	v_cvt_scalef32_pk_f16_fp8 v83, v180, 1.0 op_sel:[1,0,0]
	v_cvt_scalef32_pk_f16_fp8 v84, v181, 1.0
	v_cvt_scalef32_pk_f16_fp8 v85, v181, 1.0 op_sel:[1,0,0]
	v_cvt_scalef32_pk_f16_fp8 v110, v158, 1.0
	v_cvt_scalef32_pk_f16_fp8 v111, v158, 1.0 op_sel:[1,0,0]
	v_cvt_scalef32_pk_f16_fp8 v112, v159, 1.0
	v_cvt_scalef32_pk_f16_fp8 v113, v159, 1.0 op_sel:[1,0,0]
	v_cvt_scalef32_pk_f16_fp8 v106, v156, 1.0
	v_cvt_scalef32_pk_f16_fp8 v107, v156, 1.0 op_sel:[1,0,0]
	v_cvt_scalef32_pk_f16_fp8 v108, v157, 1.0
	v_cvt_scalef32_pk_f16_fp8 v109, v157, 1.0 op_sel:[1,0,0]
	v_cvt_scalef32_pk_f16_fp8 v98, v126, 1.0
	v_cvt_scalef32_pk_f16_fp8 v99, v126, 1.0 op_sel:[1,0,0]
	v_cvt_scalef32_pk_f16_fp8 v100, v127, 1.0
	v_cvt_scalef32_pk_f16_fp8 v101, v127, 1.0 op_sel:[1,0,0]
	global_load_dwordx2 v[188:189], v[122:123], off
	global_load_dwordx2 v[186:187], v[122:123], off offset:512
	global_load_dwordx2 v[184:185], v[122:123], off offset:1024
	global_load_dwordx2 v[180:181], v[122:123], off offset:1536
	global_load_dwordx2 v[158:159], v[122:123], off offset:2048
	global_load_dwordx2 v[156:157], v[122:123], off offset:2560
	global_load_dwordx2 v[126:127], v[122:123], off offset:3072
	s_nop 0
	global_load_dwordx2 v[122:123], v[122:123], off offset:3584
	s_add_i32 s100, s12, 64
	s_lshr_b32 s33, s13, 8
	s_andn2_b64 vcc, exec, s[10:11]
	v_subrev_u32_e32 v226, s12, v213
	s_cbranch_vccnz .LBB0_938
	s_cmp_le_u32 s100, s93
	s_cbranch_scc1 .Lsel_fast0
	v_lshrrev_b32_e64 v227, v192, s33
	v_and_b32_e32 v227, 1, v227
	v_add_u32_e32 v228, v226, v223
	v_cmp_eq_u32_e32 vcc, 1, v227
	v_max_f32_e32 v230, v63, v63
	s_nop 0
	v_cndmask_b32_e32 v227, -1, v228, vcc
	v_max_f32_e32 v228, 0xf149f2ca, v54
	v_cmp_gt_i32_e64 s[42:43], 0, v227
	v_cmp_gt_i32_e64 s[40:41], 1, v227
	v_cmp_gt_i32_e64 s[38:39], 2, v227
	v_cndmask_b32_e64 v228, v228, v172, s[42:43]
	v_max_f32_e32 v229, v228, v55
	v_cndmask_b32_e64 v228, v229, v228, s[40:41]
	v_max_f32_e32 v229, v228, v56
	v_cndmask_b32_e64 v228, v229, v228, s[38:39]
	v_max_f32_e32 v229, v228, v57
	v_cmp_gt_i32_e64 s[36:37], 3, v227
	v_cmp_gt_i32_e64 s[34:35], 16, v227
	v_cmp_gt_i32_e64 s[30:31], 17, v227
	v_cndmask_b32_e64 v228, v229, v228, s[36:37]
	v_max_f32_e32 v229, v228, v62
	v_cndmask_b32_e64 v228, v229, v228, s[34:35]
	v_max_f32_e32 v229, v228, v230
	v_cndmask_b32_e64 v228, v229, v228, s[30:31]
	v_max_f32_e32 v230, v64, v64
	v_max_f32_e32 v229, v228, v230
	v_cmp_gt_i32_e64 s[28:29], 18, v227
	v_max_f32_e32 v230, v65, v65
	v_cmp_gt_i32_e64 s[26:27], 19, v227
	v_cndmask_b32_e64 v228, v229, v228, s[28:29]
	v_max_f32_e32 v229, v228, v230
	v_cndmask_b32_e64 v228, v229, v228, s[26:27]
	v_max_f32_e32 v230, v70, v70
	v_max_f32_e32 v229, v228, v230
	v_cmp_gt_i32_e64 s[24:25], 32, v227
	v_max_f32_e32 v230, v71, v71
	v_cmp_gt_i32_e64 s[22:23], 33, v227
	v_cndmask_b32_e64 v228, v229, v228, s[24:25]
	v_max_f32_e32 v229, v228, v230
	v_cndmask_b32_e64 v228, v229, v228, s[22:23]
	v_max_f32_e32 v230, v72, v72
	v_max_f32_e32 v229, v228, v230
	v_cmp_gt_i32_e64 s[20:21], 34, v227
	v_max_f32_e32 v230, v73, v73
	v_cmp_gt_i32_e64 s[18:19], 35, v227
	v_cndmask_b32_e64 v228, v229, v228, s[20:21]
	v_max_f32_e32 v229, v228, v230
	v_cndmask_b32_e64 v228, v229, v228, s[18:19]
	v_max_f32_e32 v230, v78, v78
	v_max_f32_e32 v229, v228, v230
	v_cmp_gt_i32_e64 s[16:17], 48, v227
	v_max_f32_e32 v230, v79, v79
	v_cmp_gt_i32_e64 s[14:15], 49, v227
	v_cndmask_b32_e64 v228, v229, v228, s[16:17]
	v_max_f32_e32 v229, v228, v230
	v_cndmask_b32_e64 v228, v229, v228, s[14:15]
	v_max_f32_e32 v230, v80, v80
	v_max_f32_e32 v229, v228, v230
	v_cmp_gt_i32_e64 s[12:13], 50, v227
	v_max_f32_e32 v230, v81, v81
	v_cmp_gt_i32_e64 s[10:11], 51, v227
	v_cndmask_b32_e64 v228, v229, v228, s[12:13]
	v_max_f32_e32 v229, v228, v230
	v_cndmask_b32_e64 v227, v229, v228, s[10:11]
	v_add_f32_e32 v228, 0x41400000, v225
	v_cmp_gt_f32_e32 vcc, v227, v228
	s_cbranch_vccz .LBB0_937
	ds_bpermute_b32 v228, v173, v227
	v_max_f32_e32 v227, v227, v227
	s_waitcnt lgkmcnt(0)
	v_max_f32_e32 v228, v228, v228
	v_max_f32_e32 v227, v227, v228
	ds_bpermute_b32 v228, v222, v227
	s_waitcnt lgkmcnt(0)
	v_max3_f32 v227, v225, v227, v228
	v_sub_f32_e32 v225, v225, v227
	v_exp_f32_e32 v228, v225
	v_mov_b32_e32 v225, v227
	v_mul_f32_e32 v149, v149, v228
	v_pk_mul_f32 v[28:29], v[28:29], v[228:229] op_sel_hi:[1,0]
	v_pk_mul_f32 v[26:27], v[26:27], v[228:229] op_sel_hi:[1,0]
	v_pk_mul_f32 v[32:33], v[32:33], v[228:229] op_sel_hi:[1,0]
	v_pk_mul_f32 v[30:31], v[30:31], v[228:229] op_sel_hi:[1,0]
	v_pk_mul_f32 v[24:25], v[24:25], v[228:229] op_sel_hi:[1,0]
	v_pk_mul_f32 v[22:23], v[22:23], v[228:229] op_sel_hi:[1,0]
	v_pk_mul_f32 v[20:21], v[20:21], v[228:229] op_sel_hi:[1,0]
	v_pk_mul_f32 v[18:19], v[18:19], v[228:229] op_sel_hi:[1,0]

; __device__ __forceinline__ float shx(float v, int m) { return __shfl_xor(v, m); }
; template <class KB>
; __device__ __forceinline__ void sel_run(int nit, KB kbof, const half8 (&qf)[2][2], const unsigned char* kf, const unsigned char* vf, const int (&tqs)[2], int qq,
;                                         f32x4 (&o)[2][4], float (&m)[2], float (&l)[2], int g) {
;     ...
; #pragma unroll
;         for (int s_ = 0; s_ < 2; ++s_)
;             if (need[s_]) {
;                 float p[4][4]; float mx = -1e30f;
;                 const int klim = selq[s_] ? tqs[s_] - kbA - 4 * g : -1;
; #pragma unroll
;                 for (int t = 0; t < 4; ++t)
; #pragma unroll
;                     for (int r = 0; r < 4; ++r) { if (16 * t + r <= klim) mx = fmaxf(mx, s[s_][t][r]); }
;                 if (__ballot(mx > m[s_] + RESC_THR) != 0ull) {
;                     mx = fmaxf(mx, shx(mx, 16)); mx = fmaxf(mx, shx(mx, 32));
;                     const float mn = fmaxf(m[s_], mx); const float corr = __builtin_amdgcn_exp2f(m[s_] - mn); m[s_] = mn;
;                     l[s_] = l[s_] * corr;
; #pragma unroll
;                     for (int dt = 0; dt < 4; ++dt) o[s_][dt] = o[s_][dt] * corr;
;                 }
.LBB0_938:
	s_andn2_b64 vcc, exec, s[2:3]
	s_cbranch_vccnz .LBB0_942
	s_cmp_le_u32 s100, s93
	s_cbranch_scc1 .Lsel_fast1
	v_lshrrev_b32_e64 v227, v214, s33
	v_and_b32_e32 v227, 1, v227
	v_add_u32_e32 v226, v226, v224
	v_cmp_eq_u32_e32 vcc, 1, v227
	v_max_f32_e32 v227, 0xf149f2ca, v50
	s_nop 0
	v_cndmask_b32_e32 v226, -1, v226, vcc
	v_cmp_gt_i32_e64 s[42:43], 0, v226
	v_cmp_gt_i32_e64 s[40:41], 1, v226
	s_nop 0
	v_cndmask_b32_e64 v227, v227, v172, s[42:43]
	v_max_f32_e32 v228, v227, v51
	v_cndmask_b32_e64 v227, v228, v227, s[40:41]
	v_max_f32_e32 v228, v227, v52
	v_cmp_gt_i32_e64 s[38:39], 2, v226
	v_cmp_gt_i32_e64 s[36:37], 3, v226
	v_cmp_gt_i32_e64 s[34:35], 16, v226
	v_cndmask_b32_e64 v227, v228, v227, s[38:39]
	v_max_f32_e32 v228, v227, v53
	v_cndmask_b32_e64 v227, v228, v227, s[36:37]
	v_max_f32_e32 v228, v227, v58
	v_cndmask_b32_e64 v227, v228, v227, s[34:35]
	v_max_f32_e32 v229, v59, v59
	v_max_f32_e32 v228, v227, v229
	v_cmp_gt_i32_e64 s[30:31], 17, v226
	v_max_f32_e32 v229, v60, v60
	v_cmp_gt_i32_e64 s[28:29], 18, v226
	v_cndmask_b32_e64 v227, v228, v227, s[30:31]
	v_max_f32_e32 v228, v227, v229
	v_cndmask_b32_e64 v227, v228, v227, s[28:29]
	v_max_f32_e32 v229, v61, v61
	v_max_f32_e32 v228, v227, v229
	v_cmp_gt_i32_e64 s[26:27], 19, v226
	v_max_f32_e32 v229, v66, v66
	v_cmp_gt_i32_e64 s[24:25], 32, v226
	v_cndmask_b32_e64 v227, v228, v227, s[26:27]
	v_max_f32_e32 v228, v227, v229
	v_cndmask_b32_e64 v227, v228, v227, s[24:25]
	v_max_f32_e32 v229, v67, v67
	v_max_f32_e32 v228, v227, v229
	v_cmp_gt_i32_e64 s[22:23], 33, v226
	v_max_f32_e32 v229, v68, v68
	v_cmp_gt_i32_e64 s[20:21], 34, v226
	v_cndmask_b32_e64 v227, v228, v227, s[22:23]
	v_max_f32_e32 v228, v227, v229
	v_cndmask_b32_e64 v227, v228, v227, s[20:21]
	v_max_f32_e32 v229, v69, v69
	v_max_f32_e32 v228, v227, v229
	v_cmp_gt_i32_e64 s[18:19], 35, v226
	v_max_f32_e32 v229, v74, v74
	v_cmp_gt_i32_e64 s[16:17], 48, v226
	v_cndmask_b32_e64 v227, v228, v227, s[18:19]
	v_max_f32_e32 v228, v227, v229
	v_cndmask_b32_e64 v227, v228, v227, s[16:17]
	v_max_f32_e32 v229, v75, v75
	v_max_f32_e32 v228, v227, v229
	v_cmp_gt_i32_e64 s[14:15], 49, v226
	v_max_f32_e32 v229, v76, v76
	v_cmp_gt_i32_e64 s[12:13], 50, v226
	v_cndmask_b32_e64 v227, v228, v227, s[14:15]
	v_max_f32_e32 v228, v227, v229
	v_cndmask_b32_e64 v227, v228, v227, s[12:13]
	v_max_f32_e32 v229, v77, v77
	v_max_f32_e32 v228, v227, v229
	v_cmp_gt_i32_e64 s[10:11], 51, v226
	s_nop 1
	v_cndmask_b32_e64 v226, v228, v227, s[10:11]
	v_add_f32_e32 v227, 0x41400000, v151
	v_cmp_gt_f32_e32 vcc, v226, v227
	s_cbranch_vccz .LBB0_941
	ds_bpermute_b32 v227, v173, v226
	v_max_f32_e32 v226, v226, v226
	s_waitcnt lgkmcnt(0)
	v_max_f32_e32 v227, v227, v227
	v_max_f32_e32 v226, v226, v227
	ds_bpermute_b32 v227, v222, v226
	s_waitcnt lgkmcnt(0)
	v_max3_f32 v227, v151, v226, v227
	v_sub_f32_e32 v151, v151, v227
	v_exp_f32_e32 v226, v151
	v_mov_b32_e32 v151, v227
	v_mul_f32_e32 v147, v147, v226
	v_pk_mul_f32 v[16:17], v[16:17], v[226:227] op_sel_hi:[1,0]
	v_pk_mul_f32 v[14:15], v[14:15], v[226:227] op_sel_hi:[1,0]
	v_pk_mul_f32 v[12:13], v[12:13], v[226:227] op_sel_hi:[1,0]
	v_pk_mul_f32 v[10:11], v[10:11], v[226:227] op_sel_hi:[1,0]
	v_pk_mul_f32 v[8:9], v[8:9], v[226:227] op_sel_hi:[1,0]
	v_pk_mul_f32 v[6:7], v[6:7], v[226:227] op_sel_hi:[1,0]
	v_pk_mul_f32 v[4:5], v[4:5], v[226:227] op_sel_hi:[1,0]
	v_pk_mul_f32 v[2:3], v[2:3], v[226:227] op_sel_hi:[1,0]

; #define MFMA16(a, b, c) __builtin_amdgcn_mfma_f32_16x16x32_f16((a), (b), (c), 0, 0, 0)
; __device__ __forceinline__ float shx(float v, int m) { return __shfl_xor(v, m); }
;     ...
;         for (int s_ = 0; s_ < NS; ++s_) {
;             f32x4 s[4];
; #pragma unroll
;             for (int t = 0; t < 4; ++t) { s[t] = MFMA16(ka[2 * t], qf[s_][0], z); s[t] = MFMA16(ka[2 * t + 1], qf[s_][1], s[t]); }
;             if (s_ == NS - 1) {
;                 const half_t* kpA = kf + (size_t)nbA * 2048; const half_t* kpB = kf + (size_t)nbB * 2048;
; #pragma unroll
;                 for (int i = 0; i < 4; ++i) { ka[i] = *(const half8*)(kpA + i * 512); ka[4 + i] = *(const half8*)(kpB + i * 512); }
;             }
;             if (MODE != 1) {
;                 float mx = -1e30f;
; #pragma unroll
;                 for (int t = 0; t < 4; ++t)
; #pragma unroll
;                     for (int r = 0; r < 4; ++r) { if (valid(s_, kbA + 16 * t + 4 * g + r)) mx = fmaxf(mx, s[t][r]); }
;                 if (__ballot(mx > m[s_] + RESC_THR) != 0ull) {
;                     mx = fmaxf(mx, shx(mx, 16)); mx = fmaxf(mx, shx(mx, 32));
;                     const float mn = fmaxf(m[s_], mx); const float corr = __builtin_amdgcn_exp2f(m[s_] - mn); m[s_] = mn; l[s_] = l[s_] * corr;
;                     if (PV) {
; #pragma unroll
;                         for (int dt = 0; dt < 4; ++dt) o[s_][dt] = o[s_][dt] * corr;
;                     }
;                 }
;             }
.LBB0_947:
	global_load_dwordx4 v[106:109], v[82:83], off
	global_load_dwordx4 v[98:101], v[82:83], off offset:1024
	global_load_dwordx4 v[90:93], v[82:83], off offset:2048
	s_nop 0
	global_load_dwordx4 v[82:85], v[82:83], off offset:3072
	s_nop 0
	global_load_dwordx4 v[110:113], v[86:87], off
	global_load_dwordx4 v[102:105], v[86:87], off offset:1024
	global_load_dwordx4 v[94:97], v[86:87], off offset:2048
	s_nop 0
	global_load_dwordx4 v[86:89], v[86:87], off offset:3072
	s_waitcnt vmcnt(8) lgkmcnt(0)
	v_mfma_f32_16x16x32_f16 v[114:117], v[70:73], v[34:37], 0
	v_add_u32_e32 v158, s49, v166
	v_cmp_le_i32_e32 vcc, v158, v149
	v_cmp_gt_i32_e64 s[10:11], v158, v162
	v_mfma_f32_16x16x32_f16 v[126:129], v[78:81], v[38:41], v[114:117]
	s_and_b64 s[10:11], vcc, s[10:11]
	v_sub_u32_e32 v160, v158, v149
	s_movk_i32 s2, 0xfdff
	v_cmp_lt_i32_e32 vcc, v158, v149
	v_cmp_lt_i32_e64 s[12:13], s2, v160
	s_nop 2
	v_max_f32_e32 v159, 0xf149f2ca, v126
	v_cndmask_b32_e64 v159, v172, v159, s[10:11]
	v_mfma_f32_16x16x32_f16 v[114:117], v[74:77], v[34:37], 0
	s_and_b64 s[12:13], vcc, s[12:13]
	v_max_f32_e32 v160, v159, v127
	v_cndmask_b32_e64 v159, v159, v160, s[12:13]
	v_add_u32_e32 v160, 2, v158
	v_cmp_le_i32_e32 vcc, v160, v149
	v_cmp_gt_i32_e64 s[14:15], v160, v162
	s_and_b64 s[14:15], vcc, s[14:15]
	v_max_f32_e32 v160, v159, v128
	v_mfma_f32_16x16x32_f16 v[122:125], v[66:69], v[38:41], v[114:117]
	v_cndmask_b32_e64 v159, v159, v160, s[14:15]
	v_add_u32_e32 v160, 3, v158
	v_cmp_le_i32_e32 vcc, v160, v149
	v_cmp_gt_i32_e64 s[16:17], v160, v162
	s_and_b64 s[18:19], vcc, s[16:17]
	v_max_f32_e32 v160, v159, v129
	v_cndmask_b32_e64 v159, v159, v160, s[18:19]
	v_add_u32_e32 v160, 16, v158
	v_cmp_le_i32_e32 vcc, v160, v149
	v_cmp_gt_i32_e64 s[16:17], v160, v162
	s_and_b64 s[16:17], vcc, s[16:17]
	v_max_f32_e32 v160, v159, v122
	v_cndmask_b32_e64 v159, v159, v160, s[16:17]
	v_add_u32_e32 v160, 17, v158
	v_cmp_le_i32_e32 vcc, v160, v149
	v_cmp_gt_i32_e64 s[20:21], v160, v162
	v_max_f32_e32 v161, v123, v123
	v_mfma_f32_16x16x32_f16 v[114:117], v[62:65], v[34:37], 0
	s_and_b64 s[20:21], vcc, s[20:21]
	v_max_f32_e32 v160, v159, v161
	v_cndmask_b32_e64 v159, v159, v160, s[20:21]
	v_add_u32_e32 v160, 18, v158
	v_cmp_le_i32_e32 vcc, v160, v149
	v_cmp_gt_i32_e64 s[22:23], v160, v162
	v_max_f32_e32 v161, v124, v124
	s_and_b64 s[22:23], vcc, s[22:23]
	v_max_f32_e32 v160, v159, v161
	v_mfma_f32_16x16x32_f16 v[118:121], v[58:61], v[38:41], v[114:117]
	v_cndmask_b32_e64 v159, v159, v160, s[22:23]
	v_add_u32_e32 v160, 19, v158
	v_cmp_le_i32_e32 vcc, v160, v149
	v_cmp_gt_i32_e64 s[24:25], v160, v162
	v_max_f32_e32 v161, v125, v125
	s_and_b64 s[26:27], vcc, s[24:25]
	v_max_f32_e32 v160, v159, v161
	v_cndmask_b32_e64 v159, v159, v160, s[26:27]
	v_add_u32_e32 v160, 32, v158
	v_cmp_le_i32_e32 vcc, v160, v149
	v_cmp_gt_i32_e64 s[24:25], v160, v162
	v_max_f32_e32 v161, v118, v118
	s_and_b64 s[24:25], vcc, s[24:25]
	v_max_f32_e32 v160, v159, v161
	v_cndmask_b32_e64 v159, v159, v160, s[24:25]
	v_add_u32_e32 v160, 33, v158
	v_cmp_le_i32_e32 vcc, v160, v149
	v_cmp_gt_i32_e64 s[28:29], v160, v162
	v_max_f32_e32 v161, v119, v119
	v_mfma_f32_16x16x32_f16 v[114:117], v[54:57], v[34:37], 0
	s_and_b64 s[28:29], vcc, s[28:29]
	v_max_f32_e32 v160, v159, v161
	v_cndmask_b32_e64 v159, v159, v160, s[28:29]
	v_add_u32_e32 v160, 34, v158
	v_cmp_le_i32_e32 vcc, v160, v149
	v_cmp_gt_i32_e64 s[30:31], v160, v162
	v_max_f32_e32 v161, v120, v120
	s_and_b64 s[30:31], vcc, s[30:31]
	v_max_f32_e32 v160, v159, v161
	v_mfma_f32_16x16x32_f16 v[114:117], v[50:53], v[38:41], v[114:117]
	v_cndmask_b32_e64 v159, v159, v160, s[30:31]
	v_add_u32_e32 v160, 35, v158
	v_cmp_le_i32_e32 vcc, v160, v149
	v_cmp_gt_i32_e64 s[34:35], v160, v162
	v_max_f32_e32 v161, v121, v121
	s_and_b64 s[36:37], vcc, s[34:35]
	v_max_f32_e32 v160, v159, v161
	v_cndmask_b32_e64 v159, v159, v160, s[36:37]
	v_add_u32_e32 v160, 48, v158
	v_cmp_le_i32_e32 vcc, v160, v149
	v_cmp_gt_i32_e64 s[34:35], v160, v162
	v_max_f32_e32 v161, v114, v114
	s_and_b64 s[34:35], vcc, s[34:35]
	v_max_f32_e32 v160, v159, v161
	v_cndmask_b32_e64 v159, v159, v160, s[34:35]
	v_add_u32_e32 v160, 49, v158
	v_cmp_le_i32_e32 vcc, v160, v149
	v_cmp_gt_i32_e64 s[38:39], v160, v162
	v_max_f32_e32 v161, v115, v115
	s_and_b64 s[38:39], vcc, s[38:39]
	v_max_f32_e32 v160, v159, v161
	v_cndmask_b32_e64 v159, v159, v160, s[38:39]
	v_add_u32_e32 v160, 50, v158
	v_cmp_le_i32_e32 vcc, v160, v149
	v_cmp_gt_i32_e64 s[40:41], v160, v162
	v_max_f32_e32 v161, v116, v116
	s_and_b64 s[40:41], vcc, s[40:41]
	v_max_f32_e32 v160, v159, v161
	v_cndmask_b32_e64 v159, v159, v160, s[40:41]
	v_add_u32_e32 v158, 51, v158
	v_cmp_le_i32_e32 vcc, v158, v149
	v_cmp_gt_i32_e64 s[42:43], v158, v162
	v_max_f32_e32 v160, v117, v117
	s_and_b64 s[42:43], vcc, s[42:43]
	v_max_f32_e32 v158, v159, v160
	v_cndmask_b32_e64 v158, v159, v158, s[42:43]
	v_add_f32_e32 v159, 0x41400000, v168
	v_cmp_gt_f32_e32 vcc, v158, v159
	s_cbranch_vccz .LBB0_949
	ds_bpermute_b32 v159, v173, v158
	v_max_f32_e32 v158, v158, v158
	s_waitcnt lgkmcnt(0)
	v_max_f32_e32 v159, v159, v159
	v_max_f32_e32 v158, v158, v159
	ds_bpermute_b32 v159, v222, v158
	s_waitcnt lgkmcnt(0)
	v_max3_f32 v159, v168, v158, v159
	v_sub_f32_e32 v158, v168, v159
	v_exp_f32_e32 v158, v158
	v_mov_b32_e32 v168, v159
	v_mul_f32_e32 v151, v151, v158
	v_pk_mul_f32 v[32:33], v[32:33], v[158:159] op_sel_hi:[1,0]
	v_pk_mul_f32 v[30:31], v[30:31], v[158:159] op_sel_hi:[1,0]
	v_pk_mul_f32 v[28:29], v[28:29], v[158:159] op_sel_hi:[1,0]
	v_pk_mul_f32 v[26:27], v[26:27], v[158:159] op_sel_hi:[1,0]
	v_pk_mul_f32 v[24:25], v[24:25], v[158:159] op_sel_hi:[1,0]
	v_pk_mul_f32 v[22:23], v[22:23], v[158:159] op_sel_hi:[1,0]
	v_pk_mul_f32 v[20:21], v[20:21], v[158:159] op_sel_hi:[1,0]
	v_pk_mul_f32 v[18:19], v[18:19], v[158:159] op_sel_hi:[1,0]
; #define MFMA16(a, b, c) __builtin_amdgcn_mfma_f32_16x16x32_f16((a), (b), (c), 0, 0, 0)
; __device__ __forceinline__ float shx(float v, int m) { return __shfl_xor(v, m); }
;     ...
;         for (int s_ = 0; s_ < NS; ++s_) {
;             f32x4 s[4];
; #pragma unroll
;             for (int t = 0; t < 4; ++t) { s[t] = MFMA16(ka[2 * t], qf[s_][0], z); s[t] = MFMA16(ka[2 * t + 1], qf[s_][1], s[t]); }
;             if (s_ == NS - 1) {
;                 const half_t* kpA = kf + (size_t)nbA * 2048; const half_t* kpB = kf + (size_t)nbB * 2048;
; #pragma unroll
;                 for (int i = 0; i < 4; ++i) { ka[i] = *(const half8*)(kpA + i * 512); ka[4 + i] = *(const half8*)(kpB + i * 512); }
;             }
;             if (MODE != 1) {
;                 float mx = -1e30f;
; #pragma unroll
;                 for (int t = 0; t < 4; ++t)
; #pragma unroll
;                     for (int r = 0; r < 4; ++r) { if (valid(s_, kbA + 16 * t + 4 * g + r)) mx = fmaxf(mx, s[t][r]); }
;                 if (__ballot(mx > m[s_] + RESC_THR) != 0ull) {
;                     mx = fmaxf(mx, shx(mx, 16)); mx = fmaxf(mx, shx(mx, 32));
;                     const float mn = fmaxf(m[s_], mx); const float corr = __builtin_amdgcn_exp2f(m[s_] - mn); m[s_] = mn; l[s_] = l[s_] * corr;
;                     if (PV) {
; #pragma unroll
;                         for (int dt = 0; dt < 4; ++dt) o[s_][dt] = o[s_][dt] * corr;
;                     }
;                 }
;             }
;             float p[4][4]; float ps = 0.f;
; #pragma unroll
;             for (int t = 0; t < 4; ++t)
; #pragma unroll
;                 for (int r = 0; r < 4; ++r) { p[t][r] = valid(s_, kbA + 16 * t + 4 * g + r) ? __builtin_amdgcn_exp2f(s[t][r] - m[s_]) : 0.f; if (MODE == 1) p[t][r] *= l[s_]; ps += p[t][r]; }
;             if (MODE != 1) l[s_] = l[s_] + ps;
;             if (PV) {
;                 const half8 pfA = {(half_t)p[0][0], (half_t)p[0][1], (half_t)p[0][2], (half_t)p[0][3], (half_t)p[1][0], (half_t)p[1][1], (half_t)p[1][2], (half_t)p[1][3]};
;                 const half8 pfB = {(half_t)p[2][0], (half_t)p[2][1], (half_t)p[2][2], (half_t)p[2][3], (half_t)p[3][0], (half_t)p[3][1], (half_t)p[3][2], (half_t)p[3][3]};
; #pragma unroll
;                 for (int dt = 0; dt < 4; ++dt) { o[s_][dt] = MFMA16(va[dt], pfA, o[s_][dt]); o[s_][dt] = MFMA16(va[4 + dt], pfB, o[s_][dt]); }
.LBB0_949:
	v_sub_f32_e32 v126, v126, v168
	v_sub_f32_e32 v122, v122, v168
	v_exp_f32_e32 v126, v126
	v_exp_f32_e32 v122, v122
	v_sub_f32_e32 v114, v114, v168
	v_exp_f32_e32 v114, v114
	v_sub_f32_e32 v118, v118, v168
	v_cndmask_b32_e64 v169, 0, v126, s[10:11]
	v_sub_f32_e32 v126, v127, v168
	v_cndmask_b32_e64 v183, 0, v122, s[16:17]
	v_sub_f32_e32 v122, v123, v168
	v_exp_f32_e32 v118, v118
	v_exp_f32_e32 v126, v126
	v_exp_f32_e32 v122, v122
	v_cndmask_b32_e64 v224, 0, v114, s[34:35]
	v_sub_f32_e32 v114, v115, v168
	v_exp_f32_e32 v114, v114
	v_cndmask_b32_e64 v187, 0, v118, s[24:25]
	v_sub_f32_e32 v118, v119, v168
	v_cndmask_b32_e64 v180, 0, v126, s[12:13]
	v_sub_f32_e32 v126, v128, v168
	v_cndmask_b32_e64 v184, 0, v122, s[20:21]
	v_sub_f32_e32 v122, v124, v168
	v_exp_f32_e32 v118, v118
	v_exp_f32_e32 v126, v126
	v_exp_f32_e32 v122, v122
	v_cndmask_b32_e64 v225, 0, v114, s[38:39]
	v_sub_f32_e32 v114, v116, v168
	v_exp_f32_e32 v114, v114
	v_cndmask_b32_e64 v188, 0, v118, s[28:29]
	v_sub_f32_e32 v118, v120, v168
	v_cndmask_b32_e64 v181, 0, v126, s[14:15]
	v_sub_f32_e32 v126, v129, v168
	v_cndmask_b32_e64 v185, 0, v122, s[22:23]
	v_sub_f32_e32 v122, v125, v168
	v_exp_f32_e32 v118, v118
	v_exp_f32_e32 v126, v126
	v_exp_f32_e32 v122, v122
	v_cndmask_b32_e64 v226, 0, v114, s[40:41]
	v_sub_f32_e32 v114, v117, v168
	v_exp_f32_e32 v114, v114
	s_add_i32 s50, s48, 1
	v_cndmask_b32_e64 v189, 0, v118, s[30:31]
	v_sub_f32_e32 v118, v121, v168
	s_cmp_lt_i32 s48, s46
	v_cndmask_b32_e64 v182, 0, v126, s[18:19]
	v_cndmask_b32_e64 v186, 0, v122, s[26:27]
	v_exp_f32_e32 v118, v118
	s_cselect_b32 s2, s50, s48
	v_cndmask_b32_e64 v227, 0, v114, s[42:43]
	v_cvt_pk_f16_f32 v117, v185, v186
	v_cvt_pk_f16_f32 v116, v183, v184
	v_cvt_pk_f16_f32 v115, v181, v182
	v_cvt_pk_f16_f32 v114, v169, v180
	s_lshl_b32 s2, s2, 6
	v_mfma_f32_16x16x32_f16 v[70:73], v[70:73], v[42:45], 0
	s_add_i32 s49, s2, s47
	s_ashr_i32 s2, s49, 5
	v_cndmask_b32_e64 v223, 0, v118, s[36:37]
	s_waitcnt vmcnt(0)
	v_mfma_f32_16x16x32_f16 v[30:33], v[106:109], v[114:117], v[30:33]
	s_min_i32 s44, s2, 0x1fe
	v_cvt_pk_f16_f32 v121, v226, v227
	v_cvt_pk_f16_f32 v120, v224, v225
	v_mfma_f32_16x16x32_f16 v[26:29], v[98:101], v[114:117], v[26:29]
	v_cvt_pk_f16_f32 v119, v189, v223
	v_cvt_pk_f16_f32 v118, v187, v188
	s_ashr_i32 s3, s2, 31
	v_mfma_f32_16x16x32_f16 v[22:25], v[90:93], v[114:117], v[22:25]
	s_ashr_i32 s45, s44, 31
	s_lshl_b64 s[2:3], s[2:3], 12
	s_lshl_b64 s[44:45], s[44:45], 12
	v_mfma_f32_16x16x32_f16 v[18:21], v[82:85], v[114:117], v[18:21]
	s_add_u32 s44, s44, 0x1000
	v_lshl_add_u64 v[158:159], v[154:155], 0, s[2:3]
	s_addc_u32 s45, s45, 0
	v_mfma_f32_16x16x32_f16 v[30:33], v[110:113], v[118:121], v[30:33]
	v_lshl_add_u64 v[160:161], v[154:155], 0, s[44:45]
	v_mfma_f32_16x16x32_f16 v[26:29], v[102:105], v[118:121], v[26:29]
	v_mfma_f32_16x16x32_f16 v[22:25], v[94:97], v[118:121], v[22:25]
	v_mfma_f32_16x16x32_f16 v[18:21], v[86:89], v[118:121], v[18:21]
	v_mfma_f32_16x16x32_f16 v[118:121], v[78:81], v[46:49], v[70:73]
	v_mfma_f32_16x16x32_f16 v[70:73], v[74:77], v[42:45], 0
	v_mfma_f32_16x16x32_f16 v[62:65], v[62:65], v[42:45], 0
	v_mfma_f32_16x16x32_f16 v[54:57], v[54:57], v[42:45], 0
	v_mfma_f32_16x16x32_f16 v[114:117], v[66:69], v[46:49], v[70:73]
	v_mfma_f32_16x16x32_f16 v[122:125], v[58:61], v[46:49], v[62:65]
	v_mfma_f32_16x16x32_f16 v[126:129], v[50:53], v[46:49], v[54:57]
	s_nop 2
	global_load_dwordx4 v[70:73], v[158:159], off
	global_load_dwordx4 v[62:65], v[160:161], off
	global_load_dwordx4 v[78:81], v[158:159], off offset:1024
	global_load_dwordx4 v[58:61], v[160:161], off offset:1024
	global_load_dwordx4 v[74:77], v[158:159], off offset:2048
	global_load_dwordx4 v[54:57], v[160:161], off offset:2048
	global_load_dwordx4 v[66:69], v[158:159], off offset:3072
	global_load_dwordx4 v[50:53], v[160:161], off offset:3072
	v_max_f32_e32 v158, 0xf149f2ca, v118
	v_cndmask_b32_e64 v158, v172, v158, s[10:11]
	v_max_f32_e32 v159, v158, v119
	v_cndmask_b32_e64 v158, v158, v159, s[12:13]
	v_max_f32_e32 v159, v158, v120
	v_cndmask_b32_e64 v158, v158, v159, s[14:15]
	v_max_f32_e32 v159, v158, v121
	v_cndmask_b32_e64 v158, v158, v159, s[18:19]
	v_max_f32_e32 v159, v158, v114
	v_cndmask_b32_e64 v158, v158, v159, s[16:17]
	v_max_f32_e32 v160, v115, v115
	v_max_f32_e32 v159, v158, v160
	v_cndmask_b32_e64 v158, v158, v159, s[20:21]
	v_max_f32_e32 v160, v116, v116
	v_max_f32_e32 v159, v158, v160
	v_cndmask_b32_e64 v158, v158, v159, s[22:23]
	v_max_f32_e32 v160, v117, v117
	v_max_f32_e32 v159, v158, v160
	v_cndmask_b32_e64 v158, v158, v159, s[26:27]
	v_max_f32_e32 v160, v122, v122
	v_max_f32_e32 v159, v158, v160
	v_cndmask_b32_e64 v158, v158, v159, s[24:25]
	v_max_f32_e32 v160, v123, v123
	v_max_f32_e32 v159, v158, v160
	v_cndmask_b32_e64 v158, v158, v159, s[28:29]
	v_max_f32_e32 v160, v124, v124
	v_max_f32_e32 v159, v158, v160
	v_cndmask_b32_e64 v158, v158, v159, s[30:31]
	v_max_f32_e32 v160, v125, v125
	v_max_f32_e32 v159, v158, v160
	v_cndmask_b32_e64 v158, v158, v159, s[36:37]
	v_max_f32_e32 v160, v126, v126
	v_max_f32_e32 v159, v158, v160
	v_cndmask_b32_e64 v158, v158, v159, s[34:35]
	v_max_f32_e32 v160, v127, v127
	v_max_f32_e32 v159, v158, v160
	v_cndmask_b32_e64 v158, v158, v159, s[38:39]
	v_max_f32_e32 v160, v128, v128
	v_max_f32_e32 v159, v158, v160
	v_cndmask_b32_e64 v158, v158, v159, s[40:41]
	v_max_f32_e32 v160, v129, v129
	v_max_f32_e32 v159, v158, v160
	v_cndmask_b32_e64 v158, v158, v159, s[42:43]
	v_add_f32_e32 v159, 0x41400000, v163
	v_cmp_gt_f32_e32 vcc, v158, v159
	s_cbranch_vccz .LBB0_951
	ds_bpermute_b32 v159, v173, v158
	v_max_f32_e32 v158, v158, v158
	s_waitcnt lgkmcnt(0)
	v_max_f32_e32 v159, v159, v159
	v_max_f32_e32 v158, v158, v159
	ds_bpermute_b32 v159, v222, v158
	s_waitcnt lgkmcnt(0)
	v_max3_f32 v159, v163, v158, v159
	v_sub_f32_e32 v158, v163, v159
	v_exp_f32_e32 v158, v158
	v_mov_b32_e32 v163, v159
	v_mul_f32_e32 v147, v147, v158
	v_pk_mul_f32 v[16:17], v[16:17], v[158:159] op_sel_hi:[1,0]
	v_pk_mul_f32 v[14:15], v[14:15], v[158:159] op_sel_hi:[1,0]
	v_pk_mul_f32 v[12:13], v[12:13], v[158:159] op_sel_hi:[1,0]
	v_pk_mul_f32 v[10:11], v[10:11], v[158:159] op_sel_hi:[1,0]
	v_pk_mul_f32 v[8:9], v[8:9], v[158:159] op_sel_hi:[1,0]
	v_pk_mul_f32 v[6:7], v[6:7], v[158:159] op_sel_hi:[1,0]
	v_pk_mul_f32 v[4:5], v[4:5], v[158:159] op_sel_hi:[1,0]
	v_pk_mul_f32 v[2:3], v[2:3], v[158:159] op_sel_hi:[1,0]

; #define MFMA16(a, b, c) __builtin_amdgcn_mfma_f32_16x16x32_f16((a), (b), (c), 0, 0, 0)
; __device__ __forceinline__ float shx(float v, int m) { return __shfl_xor(v, m); }
;     ...
;         for (int s_ = 0; s_ < NS; ++s_) {
;             f32x4 s[4];
; #pragma unroll
;             for (int t = 0; t < 4; ++t) { s[t] = MFMA16(ka[2 * t], qf[s_][0], z); s[t] = MFMA16(ka[2 * t + 1], qf[s_][1], s[t]); }
;             if (s_ == NS - 1) {
;                 const half_t* kpA = kf + (size_t)nbA * 2048; const half_t* kpB = kf + (size_t)nbB * 2048;
; #pragma unroll
;                 for (int i = 0; i < 4; ++i) { ka[i] = *(const half8*)(kpA + i * 512); ka[4 + i] = *(const half8*)(kpB + i * 512); }
;             }
;             if (MODE != 1) {
;                 float mx = -1e30f;
; #pragma unroll
;                 for (int t = 0; t < 4; ++t)
; #pragma unroll
;                     for (int r = 0; r < 4; ++r) { if (valid(s_, kbA + 16 * t + 4 * g + r)) mx = fmaxf(mx, s[t][r]); }
;                 if (__ballot(mx > m[s_] + RESC_THR) != 0ull) {
;                     mx = fmaxf(mx, shx(mx, 16)); mx = fmaxf(mx, shx(mx, 32));
;                     const float mn = fmaxf(m[s_], mx); const float corr = __builtin_amdgcn_exp2f(m[s_] - mn); m[s_] = mn; l[s_] = l[s_] * corr;
;                     if (PV) {
; #pragma unroll
;                         for (int dt = 0; dt < 4; ++dt) o[s_][dt] = o[s_][dt] * corr;
;                     }
;                 }
;             }
.LBB0_959:
	s_waitcnt vmcnt(0) lgkmcnt(0)
	v_mfma_f32_16x16x32_f16 v[86:89], v[78:81], v[34:37], 0
	flat_load_dwordx4 v[110:113], v[84:85]
	flat_load_dwordx4 v[102:105], v[84:85] offset:1024
	v_add_u32_e32 v150, s54, v166
	v_cmp_ge_i32_e32 vcc, v147, v150
	v_mfma_f32_16x16x32_f16 v[122:125], v[74:77], v[38:41], v[86:89]
	flat_load_dwordx4 v[94:97], v[84:85] offset:2048
	s_nop 1
	flat_load_dwordx4 v[86:89], v[84:85] offset:3072
	flat_load_dwordx4 v[106:109], v[82:83]
	flat_load_dwordx4 v[98:101], v[82:83] offset:1024
	flat_load_dwordx4 v[90:93], v[82:83] offset:2048
	s_nop 0
	flat_load_dwordx4 v[82:85], v[82:83] offset:3072
	v_cmp_gt_i32_e64 s[6:7], v150, v133
	v_mfma_f32_16x16x32_f16 v[114:117], v[70:73], v[34:37], 0
	s_and_b64 s[6:7], vcc, s[6:7]
	v_cmp_gt_i32_e32 vcc, v147, v150
	v_cmp_ge_i32_e64 s[8:9], v150, v133
	v_mfma_f32_16x16x32_f16 v[126:129], v[58:61], v[38:41], v[114:117]
	s_and_b64 s[8:9], vcc, s[8:9]
	v_add_u32_e32 v151, 2, v150
	v_cmp_le_i32_e32 vcc, v151, v147
	s_nop 0
	v_max_f32_e32 v114, v122, v122
	v_max_f32_e32 v118, 0xf149f2ca, v114
	v_mfma_f32_16x16x32_f16 v[114:117], v[66:69], v[34:37], 0
	v_cndmask_b32_e64 v144, v172, v118, s[6:7]
	v_cmp_gt_i32_e64 s[10:11], v151, v133
	s_and_b64 s[12:13], vcc, s[10:11]
	v_mfma_f32_16x16x32_f16 v[118:121], v[62:65], v[38:41], v[114:117]
	v_add_u32_e32 v152, 3, v150
	v_cmp_le_i32_e32 vcc, v152, v147
	v_cmp_gt_i32_e64 s[10:11], v152, v133
	s_nop 0
	v_max_f32_e32 v114, v123, v123
	v_max_f32_e32 v145, v144, v114
	v_cndmask_b32_e64 v144, v144, v145, s[8:9]
	v_max_f32_e32 v145, v144, v124
	v_cndmask_b32_e64 v144, v144, v145, s[12:13]
	v_max_f32_e32 v145, v144, v125
	s_and_b64 s[14:15], vcc, s[10:11]
	v_add_u32_e32 v155, 16, v150
	v_cndmask_b32_e64 v144, v144, v145, s[14:15]
	v_cmp_le_i32_e32 vcc, v155, v147
	v_cmp_gt_i32_e64 s[10:11], v155, v133
	v_max_f32_e32 v145, v144, v126
	s_and_b64 s[10:11], vcc, s[10:11]
	v_cndmask_b32_e64 v144, v144, v145, s[10:11]
	v_add_u32_e32 v153, 17, v150
	v_cmp_le_i32_e32 vcc, v153, v147
	v_cmp_gt_i32_e64 s[16:17], v153, v133
	v_max_f32_e32 v154, v127, v127
	v_max_f32_e32 v145, v144, v154
	s_and_b64 s[16:17], vcc, s[16:17]
	v_cndmask_b32_e64 v144, v144, v145, s[16:17]
	v_add_u32_e32 v154, 18, v150
	v_cmp_le_i32_e32 vcc, v154, v147
	v_cmp_gt_i32_e64 s[18:19], v154, v133
	v_max_f32_e32 v156, v128, v128
	v_max_f32_e32 v145, v144, v156
	s_and_b64 s[18:19], vcc, s[18:19]
	v_cndmask_b32_e64 v144, v144, v145, s[18:19]
	v_add_u32_e32 v156, 19, v150
	v_cmp_le_i32_e32 vcc, v156, v147
	v_cmp_gt_i32_e64 s[20:21], v156, v133
	v_max_f32_e32 v157, v129, v129
	v_max_f32_e32 v145, v144, v157
	s_and_b64 s[22:23], vcc, s[20:21]
	v_cndmask_b32_e64 v144, v144, v145, s[22:23]
	v_add_u32_e32 v157, 32, v150
	v_cmp_le_i32_e32 vcc, v157, v147
	v_cmp_gt_i32_e64 s[20:21], v157, v133
	v_max_f32_e32 v158, v118, v118
	v_max_f32_e32 v145, v144, v158
	s_and_b64 s[20:21], vcc, s[20:21]
	v_cndmask_b32_e64 v144, v144, v145, s[20:21]
	v_add_u32_e32 v158, 33, v150
	v_cmp_le_i32_e32 vcc, v158, v147
	v_cmp_gt_i32_e64 s[24:25], v158, v133
	v_max_f32_e32 v159, v119, v119
	v_mfma_f32_16x16x32_f16 v[114:117], v[54:57], v[34:37], 0
	v_max_f32_e32 v145, v144, v159
	s_and_b64 s[24:25], vcc, s[24:25]
	v_cndmask_b32_e64 v144, v144, v145, s[24:25]
	v_add_u32_e32 v159, 34, v150
	v_cmp_le_i32_e32 vcc, v159, v147
	v_cmp_gt_i32_e64 s[26:27], v159, v133
	v_max_f32_e32 v160, v120, v120
	v_max_f32_e32 v145, v144, v160
	s_and_b64 s[26:27], vcc, s[26:27]
	v_mfma_f32_16x16x32_f16 v[114:117], v[50:53], v[38:41], v[114:117]
	v_cndmask_b32_e64 v144, v144, v145, s[26:27]
	v_add_u32_e32 v160, 35, v150
	v_cmp_le_i32_e32 vcc, v160, v147
	v_cmp_gt_i32_e64 s[28:29], v160, v133
	v_max_f32_e32 v161, v121, v121
	v_max_f32_e32 v145, v144, v161
	s_and_b64 s[30:31], vcc, s[28:29]
	v_cndmask_b32_e64 v144, v144, v145, s[30:31]
	v_add_u32_e32 v161, 48, v150
	v_cmp_le_i32_e32 vcc, v161, v147
	v_cmp_gt_i32_e64 s[28:29], v161, v133
	v_max_f32_e32 v162, v114, v114
	v_max_f32_e32 v145, v144, v162
	s_and_b64 s[28:29], vcc, s[28:29]
	v_cndmask_b32_e64 v144, v144, v145, s[28:29]
	v_add_u32_e32 v162, 49, v150
	v_cmp_le_i32_e32 vcc, v162, v147
	v_cmp_gt_i32_e64 s[34:35], v162, v133
	v_max_f32_e32 v163, v115, v115
	v_max_f32_e32 v145, v144, v163
	s_and_b64 s[34:35], vcc, s[34:35]
	v_cndmask_b32_e64 v144, v144, v145, s[34:35]
	v_add_u32_e32 v163, 50, v150
	v_cmp_le_i32_e32 vcc, v163, v147
	v_cmp_gt_i32_e64 s[36:37], v163, v133
	v_max_f32_e32 v167, v116, v116
	v_max_f32_e32 v145, v144, v167
	s_and_b64 s[36:37], vcc, s[36:37]
	v_cndmask_b32_e64 v144, v144, v145, s[36:37]
	v_add_u32_e32 v167, 51, v150
	v_cmp_le_i32_e32 vcc, v167, v147
	v_cmp_gt_i32_e64 s[38:39], v167, v133
	v_max_f32_e32 v168, v117, v117
	v_max_f32_e32 v145, v144, v168
	s_and_b64 s[38:39], vcc, s[38:39]
	v_cndmask_b32_e64 v144, v144, v145, s[38:39]
	v_add_f32_e32 v145, 0x41400000, v136
	v_cmp_gt_f32_e32 vcc, v144, v145
	s_cbranch_vccz .LBB0_961
	ds_bpermute_b32 v145, v139, v144
	v_max_f32_e32 v144, v144, v144
	s_waitcnt lgkmcnt(0)
	v_max_f32_e32 v145, v145, v145
	v_max_f32_e32 v144, v144, v145
	ds_bpermute_b32 v145, v146, v144
	s_waitcnt lgkmcnt(0)
	v_max3_f32 v144, v136, v144, v145
	v_sub_f32_e32 v136, v136, v144
	v_exp_f32_e32 v136, v136
	v_mov_b32_e32 v145, v137
	v_mul_f32_e32 v138, v138, v136
	v_pk_mul_f32 v[32:33], v[32:33], v[136:137] op_sel_hi:[1,0]
	v_pk_mul_f32 v[30:31], v[30:31], v[136:137] op_sel_hi:[1,0]
	v_pk_mul_f32 v[28:29], v[28:29], v[136:137] op_sel_hi:[1,0]
	v_pk_mul_f32 v[26:27], v[26:27], v[136:137] op_sel_hi:[1,0]
	v_pk_mul_f32 v[24:25], v[24:25], v[136:137] op_sel_hi:[1,0]
	v_pk_mul_f32 v[22:23], v[22:23], v[136:137] op_sel_hi:[1,0]
	v_pk_mul_f32 v[20:21], v[20:21], v[136:137] op_sel_hi:[1,0]
	v_pk_mul_f32 v[18:19], v[18:19], v[136:137] op_sel_hi:[1,0]
	v_mov_b32_e32 v136, v144
	s_branch .LBB0_962

; #define MFMA16(a, b, c) __builtin_amdgcn_mfma_f32_16x16x32_f16((a), (b), (c), 0, 0, 0)
;     ...
;             float p[4][4]; float ps = 0.f;
; #pragma unroll
;             for (int t = 0; t < 4; ++t)
; #pragma unroll
;                 for (int r = 0; r < 4; ++r) { p[t][r] = valid(s_, kbA + 16 * t + 4 * g + r) ? __builtin_amdgcn_exp2f(s[t][r] - m[s_]) : 0.f; if (MODE == 1) p[t][r] *= l[s_]; ps += p[t][r]; }
;             if (MODE != 1) l[s_] = l[s_] + ps;
;             if (PV) {
;                 const half8 pfA = {(half_t)p[0][0], (half_t)p[0][1], (half_t)p[0][2], (half_t)p[0][3], (half_t)p[1][0], (half_t)p[1][1], (half_t)p[1][2], (half_t)p[1][3]};
;                 const half8 pfB = {(half_t)p[2][0], (half_t)p[2][1], (half_t)p[2][2], (half_t)p[2][3], (half_t)p[3][0], (half_t)p[3][1], (half_t)p[3][2], (half_t)p[3][3]};
; #pragma unroll
;                 for (int dt = 0; dt < 4; ++dt) { o[s_][dt] = MFMA16(va[dt], pfA, o[s_][dt]); o[s_][dt] = MFMA16(va[4 + dt], pfB, o[s_][dt]); }
.LBB0_962:
	v_sub_f32_e32 v122, v122, v136
	v_exp_f32_e32 v122, v122
	v_sub_f32_e32 v123, v123, v136
	v_sub_f32_e32 v126, v126, v136
	v_sub_f32_e32 v127, v127, v136
	v_sub_f32_e32 v128, v128, v136
	v_sub_f32_e32 v129, v129, v136
	v_exp_f32_e32 v123, v123
	v_sub_f32_e32 v124, v124, v136
	v_exp_f32_e32 v126, v126
	v_exp_f32_e32 v127, v127
	v_exp_f32_e32 v128, v128
	v_exp_f32_e32 v129, v129
	v_mfma_f32_16x16x32_f16 v[78:81], v[78:81], v[42:45], 0
	v_exp_f32_e32 v124, v124
	v_sub_f32_e32 v125, v125, v136
	v_exp_f32_e32 v125, v125
	v_cndmask_b32_e64 v122, 0, v122, s[6:7]
	v_cndmask_b32_e64 v123, 0, v123, s[8:9]
	v_cndmask_b32_e64 v173, 0, v126, s[10:11]
	v_cndmask_b32_e64 v180, 0, v127, s[16:17]
	v_cndmask_b32_e64 v181, 0, v128, s[18:19]
	v_cndmask_b32_e64 v182, 0, v129, s[22:23]
	v_sub_f32_e32 v114, v114, v136
	v_sub_f32_e32 v115, v115, v136
	v_mfma_f32_16x16x32_f16 v[126:129], v[74:77], v[46:49], v[78:81]
	v_add_f32_e32 v74, 0, v122
	v_cndmask_b32_e64 v124, 0, v124, s[12:13]
	v_exp_f32_e32 v114, v114
	v_exp_f32_e32 v115, v115
	v_sub_f32_e32 v116, v116, v136
	v_sub_f32_e32 v117, v117, v136
	v_add_f32_e32 v74, v123, v74
	v_mfma_f32_16x16x32_f16 v[70:73], v[70:73], v[42:45], 0
	v_cndmask_b32_e64 v125, 0, v125, s[14:15]
	v_sub_f32_e32 v118, v118, v136
	v_exp_f32_e32 v116, v116
	v_exp_f32_e32 v117, v117
	v_add_f32_e32 v74, v124, v74
	v_exp_f32_e32 v118, v118
	v_sub_f32_e32 v119, v119, v136
	v_add_f32_e32 v74, v125, v74
	v_exp_f32_e32 v119, v119
	v_sub_f32_e32 v120, v120, v136
	v_sub_f32_e32 v121, v121, v136
	v_add_f32_e32 v74, v173, v74
	v_exp_f32_e32 v120, v120
	v_exp_f32_e32 v121, v121
	v_cndmask_b32_e64 v187, 0, v114, s[28:29]
	v_cndmask_b32_e64 v188, 0, v115, s[34:35]
	v_cvt_pk_f16_f32 v115, v124, v125
	v_cvt_pk_f16_f32 v114, v122, v123
	v_mfma_f32_16x16x32_f16 v[122:125], v[58:61], v[46:49], v[70:73]
	v_add_f32_e32 v58, v180, v74
	v_cndmask_b32_e64 v189, 0, v116, s[36:37]
	v_cndmask_b32_e64 v190, 0, v117, s[38:39]
	v_cvt_pk_f16_f32 v117, v181, v182
	v_cvt_pk_f16_f32 v116, v173, v180
	s_add_i32 s55, s53, 1
	v_add_f32_e32 v58, v181, v58
	v_cndmask_b32_e64 v183, 0, v118, s[20:21]
	s_waitcnt vmcnt(0) lgkmcnt(0)
; #define MFMA16(a, b, c) __builtin_amdgcn_mfma_f32_16x16x32_f16((a), (b), (c), 0, 0, 0)
; __device__ __forceinline__ float shx(float v, int m) { return __shfl_xor(v, m); }
;     ...
;         for (int s_ = 0; s_ < NS; ++s_) {
;             f32x4 s[4];
; #pragma unroll
;             for (int t = 0; t < 4; ++t) { s[t] = MFMA16(ka[2 * t], qf[s_][0], z); s[t] = MFMA16(ka[2 * t + 1], qf[s_][1], s[t]); }
;             if (s_ == NS - 1) {
;                 const half_t* kpA = kf + (size_t)nbA * 2048; const half_t* kpB = kf + (size_t)nbB * 2048;
; #pragma unroll
;                 for (int i = 0; i < 4; ++i) { ka[i] = *(const half8*)(kpA + i * 512); ka[4 + i] = *(const half8*)(kpB + i * 512); }
;             }
;             if (MODE != 1) {
;                 float mx = -1e30f;
; #pragma unroll
;                 for (int t = 0; t < 4; ++t)
; #pragma unroll
;                     for (int r = 0; r < 4; ++r) { if (valid(s_, kbA + 16 * t + 4 * g + r)) mx = fmaxf(mx, s[t][r]); }
;                 if (__ballot(mx > m[s_] + RESC_THR) != 0ull) {
;                     mx = fmaxf(mx, shx(mx, 16)); mx = fmaxf(mx, shx(mx, 32));
;                     const float mn = fmaxf(m[s_], mx); const float corr = __builtin_amdgcn_exp2f(m[s_] - mn); m[s_] = mn; l[s_] = l[s_] * corr;
;                     if (PV) {
; #pragma unroll
;                         for (int dt = 0; dt < 4; ++dt) o[s_][dt] = o[s_][dt] * corr;
;                     }
;                 }
;             }
;             float p[4][4]; float ps = 0.f;
; #pragma unroll
;             for (int t = 0; t < 4; ++t)
; #pragma unroll
;                 for (int r = 0; r < 4; ++r) { p[t][r] = valid(s_, kbA + 16 * t + 4 * g + r) ? __builtin_amdgcn_exp2f(s[t][r] - m[s_]) : 0.f; if (MODE == 1) p[t][r] *= l[s_]; ps += p[t][r]; }
;             if (MODE != 1) l[s_] = l[s_] + ps;
;             if (PV) {
;                 const half8 pfA = {(half_t)p[0][0], (half_t)p[0][1], (half_t)p[0][2], (half_t)p[0][3], (half_t)p[1][0], (half_t)p[1][1], (half_t)p[1][2], (half_t)p[1][3]};
;                 const half8 pfB = {(half_t)p[2][0], (half_t)p[2][1], (half_t)p[2][2], (half_t)p[2][3], (half_t)p[3][0], (half_t)p[3][1], (half_t)p[3][2], (half_t)p[3][3]};
; #pragma unroll
;                 for (int dt = 0; dt < 4; ++dt) { o[s_][dt] = MFMA16(va[dt], pfA, o[s_][dt]); o[s_][dt] = MFMA16(va[4 + dt], pfB, o[s_][dt]); }
	v_mfma_f32_16x16x32_f16 v[30:33], v[110:113], v[114:117], v[30:33]
	s_cmp_lt_i32 s53, s52
	v_add_f32_e32 v70, v182, v58
	v_cndmask_b32_e64 v184, 0, v119, s[24:25]
	v_mfma_f32_16x16x32_f16 v[26:29], v[102:105], v[114:117], v[26:29]
	s_cselect_b32 s2, s55, s53
	v_cndmask_b32_e64 v185, 0, v120, s[26:27]
	v_cndmask_b32_e64 v186, 0, v121, s[30:31]
	v_mfma_f32_16x16x32_f16 v[22:25], v[94:97], v[114:117], v[22:25]
	s_lshl_b32 s2, s2, 6
	v_cvt_pk_f16_f32 v121, v189, v190
	v_cvt_pk_f16_f32 v120, v187, v188
	v_mfma_f32_16x16x32_f16 v[18:21], v[86:89], v[114:117], v[18:21]
	v_cvt_pk_f16_f32 v119, v185, v186
	v_cvt_pk_f16_f32 v118, v183, v184
	s_add_i32 s54, s2, s51
	v_mfma_f32_16x16x32_f16 v[58:61], v[66:69], v[42:45], 0
	v_add_f32_e32 v66, v183, v70
	v_add_f32_e32 v66, v184, v66
	v_add_f32_e32 v66, v185, v66
	v_mfma_f32_16x16x32_f16 v[30:33], v[106:109], v[118:121], v[30:33]
	s_lshr_b32 s84, s54, 5
	s_add_i32 s2, s84, 1
	s_min_i32 s6, s2, s43
	v_mfma_f32_16x16x32_f16 v[26:29], v[98:101], v[118:121], v[26:29]
	s_lshl_b64 s[2:3], s[84:85], 12
	s_ashr_i32 s7, s6, 31
	v_lshl_add_u64 v[136:137], v[140:141], 0, s[2:3]
	v_mfma_f32_16x16x32_f16 v[22:25], v[90:93], v[118:121], v[22:25]
	s_lshl_b64 s[48:49], s[6:7], 12
	v_lshl_add_u64 v[168:169], v[140:141], 0, s[48:49]
	v_cmp_le_i32_e32 vcc, v150, v148
	v_mfma_f32_16x16x32_f16 v[18:21], v[82:85], v[118:121], v[18:21]
	v_cmp_gt_i32_e64 s[6:7], v150, v149
	s_and_b64 s[38:39], vcc, s[6:7]
	v_cmp_lt_i32_e32 vcc, v150, v148
	v_mfma_f32_16x16x32_f16 v[118:121], v[62:65], v[46:49], v[58:61]
	v_cmp_ge_i32_e64 s[6:7], v150, v149
	s_and_b64 s[36:37], vcc, s[6:7]
	v_cmp_le_i32_e32 vcc, v151, v148
	v_add_f32_e32 v58, v186, v66
	v_add_f32_e32 v58, v187, v58
	v_mfma_f32_16x16x32_f16 v[54:57], v[54:57], v[42:45], 0
	v_add_f32_e32 v58, v188, v58
	v_add_f32_e32 v58, v189, v58
	v_add_f32_e32 v58, v190, v58
	v_add_f32_e32 v138, v138, v58
	v_mfma_f32_16x16x32_f16 v[114:117], v[50:53], v[46:49], v[54:57]
	flat_load_dwordx4 v[78:81], v[136:137]
	flat_load_dwordx4 v[74:77], v[136:137] offset:1024
	flat_load_dwordx4 v[66:69], v[168:169]
	flat_load_dwordx4 v[62:65], v[168:169] offset:1024
	flat_load_dwordx4 v[70:73], v[136:137] offset:2048
	flat_load_dwordx4 v[58:61], v[136:137] offset:3072
	flat_load_dwordx4 v[54:57], v[168:169] offset:2048
	flat_load_dwordx4 v[50:53], v[168:169] offset:3072
	v_max_f32_e32 v136, 0xf149f2ca, v126
	v_cndmask_b32_e64 v136, v172, v136, s[38:39]
	v_max_f32_e32 v137, v136, v127
	v_cndmask_b32_e64 v136, v136, v137, s[36:37]
	v_cmp_gt_i32_e64 s[6:7], v151, v149
	v_max_f32_e32 v137, v136, v128
	s_and_b64 s[34:35], vcc, s[6:7]
	v_cndmask_b32_e64 v136, v136, v137, s[34:35]
	v_cmp_le_i32_e32 vcc, v152, v148
	v_cmp_gt_i32_e64 s[6:7], v152, v149
	v_max_f32_e32 v137, v136, v129
	s_and_b64 s[28:29], vcc, s[6:7]
	v_cndmask_b32_e64 v136, v136, v137, s[28:29]
	v_sub_u32_e32 v137, v147, v150
	s_movk_i32 s6, 0x81
	v_cmp_le_i32_e32 vcc, v155, v148
	v_cmp_gt_i32_e64 s[6:7], s6, v137
	v_max_f32_e32 v137, v136, v122
	s_and_b64 s[30:31], vcc, s[6:7]
	v_cndmask_b32_e64 v136, v136, v137, s[30:31]
	v_cmp_le_i32_e32 vcc, v153, v148
	v_cmp_gt_i32_e64 s[6:7], v153, v149
	v_max_f32_e32 v150, v123, v123
	v_max_f32_e32 v137, v136, v150
	s_and_b64 s[26:27], vcc, s[6:7]
	v_cndmask_b32_e64 v136, v136, v137, s[26:27]
	v_cmp_le_i32_e32 vcc, v154, v148
	v_cmp_gt_i32_e64 s[6:7], v154, v149
	v_max_f32_e32 v150, v124, v124
	v_max_f32_e32 v137, v136, v150
	s_and_b64 s[24:25], vcc, s[6:7]
	v_cndmask_b32_e64 v136, v136, v137, s[24:25]
	v_cmp_le_i32_e32 vcc, v156, v148
	v_cmp_gt_i32_e64 s[6:7], v156, v149
	v_max_f32_e32 v150, v125, v125
	v_max_f32_e32 v137, v136, v150
	s_and_b64 s[20:21], vcc, s[6:7]
	v_cndmask_b32_e64 v136, v136, v137, s[20:21]
	v_cmp_le_i32_e32 vcc, v157, v148
	v_cmp_gt_i32_e64 s[6:7], v157, v149
	v_max_f32_e32 v150, v118, v118
	v_max_f32_e32 v137, v136, v150
	s_and_b64 s[22:23], vcc, s[6:7]
	v_cndmask_b32_e64 v136, v136, v137, s[22:23]
	v_cmp_le_i32_e32 vcc, v158, v148
	v_cmp_gt_i32_e64 s[6:7], v158, v149
	v_max_f32_e32 v150, v119, v119
	v_max_f32_e32 v137, v136, v150
	s_and_b64 s[18:19], vcc, s[6:7]
	v_cndmask_b32_e64 v136, v136, v137, s[18:19]
	v_cmp_le_i32_e32 vcc, v159, v148
	v_cmp_gt_i32_e64 s[6:7], v159, v149
	v_max_f32_e32 v150, v120, v120
	v_max_f32_e32 v137, v136, v150
	s_and_b64 s[16:17], vcc, s[6:7]
	v_cndmask_b32_e64 v136, v136, v137, s[16:17]
	v_cmp_le_i32_e32 vcc, v160, v148
	v_cmp_gt_i32_e64 s[6:7], v160, v149
	v_max_f32_e32 v150, v121, v121
	v_max_f32_e32 v137, v136, v150
	s_and_b64 s[12:13], vcc, s[6:7]
	v_cndmask_b32_e64 v136, v136, v137, s[12:13]
	v_cmp_le_i32_e32 vcc, v161, v148
	v_cmp_gt_i32_e64 s[6:7], v161, v149
	v_max_f32_e32 v150, v114, v114
	v_max_f32_e32 v137, v136, v150
	s_and_b64 s[14:15], vcc, s[6:7]
	v_cndmask_b32_e64 v136, v136, v137, s[14:15]
	v_cmp_le_i32_e32 vcc, v162, v148
	v_cmp_gt_i32_e64 s[6:7], v162, v149
	v_max_f32_e32 v150, v115, v115
	v_max_f32_e32 v137, v136, v150
	s_and_b64 s[10:11], vcc, s[6:7]
	v_cndmask_b32_e64 v136, v136, v137, s[10:11]
	v_cmp_le_i32_e32 vcc, v163, v148
	v_cmp_gt_i32_e64 s[6:7], v163, v149
	v_max_f32_e32 v150, v116, v116
	v_max_f32_e32 v137, v136, v150
	s_and_b64 s[8:9], vcc, s[6:7]
	v_cndmask_b32_e64 v136, v136, v137, s[8:9]
	v_cmp_le_i32_e32 vcc, v167, v148
	v_cmp_gt_i32_e64 s[6:7], v167, v149
	v_max_f32_e32 v150, v117, v117
	v_max_f32_e32 v137, v136, v150
	s_and_b64 s[6:7], vcc, s[6:7]
	v_cndmask_b32_e64 v136, v136, v137, s[6:7]
	v_add_f32_e32 v137, 0x41400000, v145
	v_cmp_gt_f32_e32 vcc, v136, v137
	s_cbranch_vccz .LBB0_964
	ds_bpermute_b32 v137, v139, v136
	v_max_f32_e32 v136, v136, v136
	s_waitcnt lgkmcnt(0)
	v_max_f32_e32 v137, v137, v137
	v_max_f32_e32 v136, v136, v137
	ds_bpermute_b32 v137, v146, v136
	s_waitcnt lgkmcnt(0)
	v_max3_f32 v151, v145, v136, v137
	v_sub_f32_e32 v136, v145, v151
	v_exp_f32_e32 v150, v136
	v_mov_b32_e32 v145, v151
	v_mov_b64_e32 v[136:137], v[144:145]
	v_mul_f32_e32 v131, v131, v150
	v_pk_mul_f32 v[16:17], v[16:17], v[150:151] op_sel_hi:[1,0]
	v_pk_mul_f32 v[14:15], v[14:15], v[150:151] op_sel_hi:[1,0]
	v_pk_mul_f32 v[12:13], v[12:13], v[150:151] op_sel_hi:[1,0]
	v_pk_mul_f32 v[10:11], v[10:11], v[150:151] op_sel_hi:[1,0]
	v_pk_mul_f32 v[8:9], v[8:9], v[150:151] op_sel_hi:[1,0]
	v_pk_mul_f32 v[6:7], v[6:7], v[150:151] op_sel_hi:[1,0]
	v_pk_mul_f32 v[4:5], v[4:5], v[150:151] op_sel_hi:[1,0]
	v_pk_mul_f32 v[2:3], v[2:3], v[150:151] op_sel_hi:[1,0]
	s_branch .LBB0_965

; #define MFMA16(a, b, c) __builtin_amdgcn_mfma_f32_16x16x32_f16((a), (b), (c), 0, 0, 0)
; __device__ __forceinline__ float shx(float v, int m) { return __shfl_xor(v, m); }
;     ...
;         for (int s_ = 0; s_ < NS; ++s_) {
;             f32x4 s[4];
; #pragma unroll
;             for (int t = 0; t < 4; ++t) { s[t] = MFMA16(ka[2 * t], qf[s_][0], z); s[t] = MFMA16(ka[2 * t + 1], qf[s_][1], s[t]); }
;             if (s_ == NS - 1) {
;                 const half_t* kpA = kf + (size_t)nbA * 2048; const half_t* kpB = kf + (size_t)nbB * 2048;
; #pragma unroll
;                 for (int i = 0; i < 4; ++i) { ka[i] = *(const half8*)(kpA + i * 512); ka[4 + i] = *(const half8*)(kpB + i * 512); }
;             }
;             if (MODE != 1) {
;                 float mx = -1e30f;
; #pragma unroll
;                 for (int t = 0; t < 4; ++t)
; #pragma unroll
;                     for (int r = 0; r < 4; ++r) { if (valid(s_, kbA + 16 * t + 4 * g + r)) mx = fmaxf(mx, s[t][r]); }
;                 if (__ballot(mx > m[s_] + RESC_THR) != 0ull) {
;                     mx = fmaxf(mx, shx(mx, 16)); mx = fmaxf(mx, shx(mx, 32));
;                     const float mn = fmaxf(m[s_], mx); const float corr = __builtin_amdgcn_exp2f(m[s_] - mn); m[s_] = mn; l[s_] = l[s_] * corr;
;                     if (PV) {
; #pragma unroll
;                         for (int dt = 0; dt < 4; ++dt) o[s_][dt] = o[s_][dt] * corr;
;                     }
;                 }
;             }
.LBB0_979:
	flat_load_dwordx4 v[130:133], v[106:107]
	flat_load_dwordx4 v[122:125], v[106:107] offset:1024
	flat_load_dwordx4 v[114:117], v[106:107] offset:2048
	s_nop 0
	flat_load_dwordx4 v[106:109], v[106:107] offset:3072
	s_nop 0
	flat_load_dwordx4 v[134:137], v[110:111]
	flat_load_dwordx4 v[126:129], v[110:111] offset:1024
	flat_load_dwordx4 v[118:121], v[110:111] offset:2048
	s_nop 0
	flat_load_dwordx4 v[110:113], v[110:111] offset:3072
	s_waitcnt vmcnt(0) lgkmcnt(0)
	v_mfma_f32_16x16x32_f16 v[138:141], v[90:93], v[50:53], 0
	v_add_u32_e32 v157, s46, v166
	v_cmp_le_i32_e32 vcc, v157, v190
	v_cmp_gt_i32_e64 s[6:7], v157, v192
	v_mfma_f32_16x16x32_f16 v[146:149], v[98:101], v[54:57], v[138:141]
	s_and_b64 s[6:7], vcc, s[6:7]
	v_sub_u32_e32 v159, v157, v190
	s_movk_i32 s2, 0xff7f
	v_cmp_lt_i32_e32 vcc, v157, v190
	v_cmp_lt_i32_e64 s[8:9], s2, v159
	s_nop 2
	v_max_f32_e32 v158, 0xf149f2ca, v146
	v_cndmask_b32_e64 v158, v172, v158, s[6:7]
	v_mfma_f32_16x16x32_f16 v[138:141], v[94:97], v[50:53], 0
	s_and_b64 s[8:9], vcc, s[8:9]
	v_max_f32_e32 v159, v158, v147
	v_cndmask_b32_e64 v158, v158, v159, s[8:9]
	v_add_u32_e32 v159, 2, v157
	v_cmp_le_i32_e32 vcc, v159, v190
	v_cmp_gt_i32_e64 s[10:11], v159, v192
	s_and_b64 s[10:11], vcc, s[10:11]
	v_max_f32_e32 v159, v158, v148
	v_mfma_f32_16x16x32_f16 v[150:153], v[102:105], v[54:57], v[138:141]
	v_cndmask_b32_e64 v158, v158, v159, s[10:11]
	v_add_u32_e32 v159, 3, v157
	v_cmp_le_i32_e32 vcc, v159, v190
	v_cmp_gt_i32_e64 s[12:13], v159, v192
	s_and_b64 s[14:15], vcc, s[12:13]
	v_max_f32_e32 v159, v158, v149
	v_cndmask_b32_e64 v158, v158, v159, s[14:15]
	v_add_u32_e32 v159, 16, v157
	v_cmp_le_i32_e32 vcc, v159, v190
	v_cmp_gt_i32_e64 s[12:13], v159, v192
	s_and_b64 s[12:13], vcc, s[12:13]
	v_max_f32_e32 v159, v158, v150
	v_cndmask_b32_e64 v158, v158, v159, s[12:13]
	v_add_u32_e32 v159, 17, v157
	v_cmp_le_i32_e32 vcc, v159, v190
	v_cmp_gt_i32_e64 s[16:17], v159, v192
	v_max_f32_e32 v160, v151, v151
	v_mfma_f32_16x16x32_f16 v[138:141], v[86:89], v[50:53], 0
	s_and_b64 s[16:17], vcc, s[16:17]
	v_max_f32_e32 v159, v158, v160
	v_cndmask_b32_e64 v158, v158, v159, s[16:17]
	v_add_u32_e32 v159, 18, v157
	v_cmp_le_i32_e32 vcc, v159, v190
	v_cmp_gt_i32_e64 s[18:19], v159, v192
	v_max_f32_e32 v160, v152, v152
	s_and_b64 s[18:19], vcc, s[18:19]
	v_max_f32_e32 v159, v158, v160
	v_mfma_f32_16x16x32_f16 v[142:145], v[82:85], v[54:57], v[138:141]
	v_cndmask_b32_e64 v158, v158, v159, s[18:19]
	v_add_u32_e32 v159, 19, v157
	v_cmp_le_i32_e32 vcc, v159, v190
	v_cmp_gt_i32_e64 s[20:21], v159, v192
	v_max_f32_e32 v160, v153, v153
	s_and_b64 s[22:23], vcc, s[20:21]
	v_max_f32_e32 v159, v158, v160
	v_cndmask_b32_e64 v158, v158, v159, s[22:23]
	v_add_u32_e32 v159, 32, v157
	v_cmp_le_i32_e32 vcc, v159, v190
	v_cmp_gt_i32_e64 s[20:21], v159, v192
	v_max_f32_e32 v160, v142, v142
	s_and_b64 s[20:21], vcc, s[20:21]
	v_max_f32_e32 v159, v158, v160
	v_cndmask_b32_e64 v158, v158, v159, s[20:21]
	v_add_u32_e32 v159, 33, v157
	v_cmp_le_i32_e32 vcc, v159, v190
	v_cmp_gt_i32_e64 s[24:25], v159, v192
	v_max_f32_e32 v160, v143, v143
	v_mfma_f32_16x16x32_f16 v[138:141], v[78:81], v[50:53], 0
	s_and_b64 s[24:25], vcc, s[24:25]
	v_max_f32_e32 v159, v158, v160
	v_cndmask_b32_e64 v158, v158, v159, s[24:25]
	v_add_u32_e32 v159, 34, v157
	v_cmp_le_i32_e32 vcc, v159, v190
	v_cmp_gt_i32_e64 s[26:27], v159, v192
	v_max_f32_e32 v160, v144, v144
	s_and_b64 s[26:27], vcc, s[26:27]
	v_max_f32_e32 v159, v158, v160
	v_mfma_f32_16x16x32_f16 v[138:141], v[74:77], v[54:57], v[138:141]
	v_cndmask_b32_e64 v158, v158, v159, s[26:27]
	v_add_u32_e32 v159, 35, v157
	v_cmp_le_i32_e32 vcc, v159, v190
	v_cmp_gt_i32_e64 s[28:29], v159, v192
	v_max_f32_e32 v160, v145, v145
	s_and_b64 s[30:31], vcc, s[28:29]
	v_max_f32_e32 v159, v158, v160
	v_cndmask_b32_e64 v158, v158, v159, s[30:31]
	v_add_u32_e32 v159, 48, v157
	v_cmp_le_i32_e32 vcc, v159, v190
	v_cmp_gt_i32_e64 s[28:29], v159, v192
	v_max_f32_e32 v160, v138, v138
	s_and_b64 s[28:29], vcc, s[28:29]
	v_max_f32_e32 v159, v158, v160
	v_cndmask_b32_e64 v158, v158, v159, s[28:29]
	v_add_u32_e32 v159, 49, v157
	v_cmp_le_i32_e32 vcc, v159, v190
	v_cmp_gt_i32_e64 s[34:35], v159, v192
	v_max_f32_e32 v160, v139, v139
	s_and_b64 s[34:35], vcc, s[34:35]
	v_max_f32_e32 v159, v158, v160
	v_cndmask_b32_e64 v158, v158, v159, s[34:35]
	v_add_u32_e32 v159, 50, v157
	v_cmp_le_i32_e32 vcc, v159, v190
	v_cmp_gt_i32_e64 s[36:37], v159, v192
	v_max_f32_e32 v160, v140, v140
	s_and_b64 s[36:37], vcc, s[36:37]
	v_max_f32_e32 v159, v158, v160
	v_cndmask_b32_e64 v158, v158, v159, s[36:37]
	v_add_u32_e32 v157, 51, v157
	v_cmp_le_i32_e32 vcc, v157, v190
	v_cmp_gt_i32_e64 s[38:39], v157, v192
	v_max_f32_e32 v159, v141, v141
	s_and_b64 s[38:39], vcc, s[38:39]
	v_max_f32_e32 v157, v158, v159
	v_cndmask_b32_e64 v157, v158, v157, s[38:39]
	v_add_f32_e32 v158, 0x41400000, v154
	v_cmp_gt_f32_e32 vcc, v157, v158
	s_cbranch_vccz .LBB0_981
	ds_bpermute_b32 v158, v173, v157
	v_max_f32_e32 v157, v157, v157
	s_waitcnt lgkmcnt(0)
	v_max_f32_e32 v158, v158, v158
	v_max_f32_e32 v157, v157, v158
	ds_bpermute_b32 v158, v188, v157
	s_waitcnt lgkmcnt(0)
	v_max3_f32 v157, v154, v157, v158
	v_sub_f32_e32 v158, v154, v157
	v_exp_f32_e32 v194, v158
	v_mov_b32_e32 v160, v156
	v_mov_b32_e32 v158, v154
	v_mov_b32_e32 v159, v155
	v_mov_b32_e32 v158, v157
	v_mul_f32_e32 v191, v191, v194
	v_pk_mul_f32 v[48:49], v[48:49], v[194:195] op_sel_hi:[1,0]
	v_pk_mul_f32 v[46:47], v[46:47], v[194:195] op_sel_hi:[1,0]
	v_pk_mul_f32 v[44:45], v[44:45], v[194:195] op_sel_hi:[1,0]
	v_pk_mul_f32 v[42:43], v[42:43], v[194:195] op_sel_hi:[1,0]
	v_pk_mul_f32 v[40:41], v[40:41], v[194:195] op_sel_hi:[1,0]
	v_pk_mul_f32 v[38:39], v[38:39], v[194:195] op_sel_hi:[1,0]
	v_pk_mul_f32 v[36:37], v[36:37], v[194:195] op_sel_hi:[1,0]
	v_pk_mul_f32 v[34:35], v[34:35], v[194:195] op_sel_hi:[1,0]
	v_mov_b32_e32 v154, v157
	s_branch .LBB0_982

; #define MFMA16(a, b, c) __builtin_amdgcn_mfma_f32_16x16x32_f16((a), (b), (c), 0, 0, 0)
; __device__ __forceinline__ float shx(float v, int m) { return __shfl_xor(v, m); }
;     ...
;         for (int s_ = 0; s_ < NS; ++s_) {
;             f32x4 s[4];
; #pragma unroll
;             for (int t = 0; t < 4; ++t) { s[t] = MFMA16(ka[2 * t], qf[s_][0], z); s[t] = MFMA16(ka[2 * t + 1], qf[s_][1], s[t]); }
;             if (s_ == NS - 1) {
;                 const half_t* kpA = kf + (size_t)nbA * 2048; const half_t* kpB = kf + (size_t)nbB * 2048;
; #pragma unroll
;                 for (int i = 0; i < 4; ++i) { ka[i] = *(const half8*)(kpA + i * 512); ka[4 + i] = *(const half8*)(kpB + i * 512); }
;             }
;             if (MODE != 1) {
;                 float mx = -1e30f;
; #pragma unroll
;                 for (int t = 0; t < 4; ++t)
; #pragma unroll
;                     for (int r = 0; r < 4; ++r) { if (valid(s_, kbA + 16 * t + 4 * g + r)) mx = fmaxf(mx, s[t][r]); }
;                 if (__ballot(mx > m[s_] + RESC_THR) != 0ull) {
;                     mx = fmaxf(mx, shx(mx, 16)); mx = fmaxf(mx, shx(mx, 32));
;                     const float mn = fmaxf(m[s_], mx); const float corr = __builtin_amdgcn_exp2f(m[s_] - mn); m[s_] = mn; l[s_] = l[s_] * corr;
;                     if (PV) {
; #pragma unroll
;                         for (int dt = 0; dt < 4; ++dt) o[s_][dt] = o[s_][dt] * corr;
;                     }
;                 }
;             }
;             float p[4][4]; float ps = 0.f;
; #pragma unroll
;             for (int t = 0; t < 4; ++t)
; #pragma unroll
;                 for (int r = 0; r < 4; ++r) { p[t][r] = valid(s_, kbA + 16 * t + 4 * g + r) ? __builtin_amdgcn_exp2f(s[t][r] - m[s_]) : 0.f; if (MODE == 1) p[t][r] *= l[s_]; ps += p[t][r]; }
;             if (MODE != 1) l[s_] = l[s_] + ps;
;             if (PV) {
;                 const half8 pfA = {(half_t)p[0][0], (half_t)p[0][1], (half_t)p[0][2], (half_t)p[0][3], (half_t)p[1][0], (half_t)p[1][1], (half_t)p[1][2], (half_t)p[1][3]};
;                 const half8 pfB = {(half_t)p[2][0], (half_t)p[2][1], (half_t)p[2][2], (half_t)p[2][3], (half_t)p[3][0], (half_t)p[3][1], (half_t)p[3][2], (half_t)p[3][3]};
; #pragma unroll
;                 for (int dt = 0; dt < 4; ++dt) { o[s_][dt] = MFMA16(va[dt], pfA, o[s_][dt]); o[s_][dt] = MFMA16(va[4 + dt], pfB, o[s_][dt]); }
.LBB0_982:
	v_sub_f32_e32 v146, v146, v154
	v_sub_f32_e32 v147, v147, v154
	v_sub_f32_e32 v148, v148, v154
	v_sub_f32_e32 v149, v149, v154
	v_exp_f32_e32 v146, v146
	v_exp_f32_e32 v147, v147
	v_exp_f32_e32 v148, v148
	v_exp_f32_e32 v149, v149
	v_cndmask_b32_e64 v193, 0, v146, s[6:7]
	v_cndmask_b32_e64 v194, 0, v147, s[8:9]
	v_cndmask_b32_e64 v195, 0, v148, s[10:11]
	v_cndmask_b32_e64 v196, 0, v149, s[14:15]
	v_sub_f32_e32 v146, v150, v154
	v_sub_f32_e32 v147, v151, v154
	v_sub_f32_e32 v148, v152, v154
	v_sub_f32_e32 v149, v153, v154
	v_exp_f32_e32 v146, v146
	v_exp_f32_e32 v147, v147
	v_exp_f32_e32 v148, v148
	v_exp_f32_e32 v149, v149
	v_sub_f32_e32 v138, v138, v154
	v_sub_f32_e32 v139, v139, v154
	v_sub_f32_e32 v140, v140, v154
	v_sub_f32_e32 v141, v141, v154
	v_exp_f32_e32 v138, v138
	v_exp_f32_e32 v139, v139
	v_exp_f32_e32 v140, v140
	v_exp_f32_e32 v141, v141
	v_cndmask_b32_e64 v197, 0, v146, s[12:13]
	v_cndmask_b32_e64 v208, 0, v147, s[16:17]
	v_cndmask_b32_e64 v209, 0, v148, s[18:19]
	v_cndmask_b32_e64 v210, 0, v149, s[22:23]
	v_cndmask_b32_e64 v215, 0, v138, s[28:29]
	v_cndmask_b32_e64 v216, 0, v139, s[34:35]
	v_cndmask_b32_e64 v217, 0, v140, s[36:37]
	v_cndmask_b32_e64 v218, 0, v141, s[38:39]
	v_cvt_pk_f16_f32 v141, v209, v210
	v_cvt_pk_f16_f32 v140, v197, v208
	v_cvt_pk_f16_f32 v139, v195, v196
	v_cvt_pk_f16_f32 v138, v193, v194
	v_sub_f32_e32 v142, v142, v154
	v_sub_f32_e32 v143, v143, v154
	s_waitcnt vmcnt(0)
	v_mfma_f32_16x16x32_f16 v[46:49], v[130:133], v[138:141], v[46:49]
	v_sub_f32_e32 v144, v144, v154
	v_sub_f32_e32 v145, v145, v154
	v_exp_f32_e32 v142, v142
	v_mfma_f32_16x16x32_f16 v[42:45], v[122:125], v[138:141], v[42:45]
	v_exp_f32_e32 v143, v143
	v_exp_f32_e32 v144, v144
	v_exp_f32_e32 v145, v145
	v_mfma_f32_16x16x32_f16 v[38:41], v[114:117], v[138:141], v[38:41]
	v_cndmask_b32_e64 v211, 0, v142, s[20:21]
	v_cndmask_b32_e64 v212, 0, v143, s[24:25]
	v_cndmask_b32_e64 v213, 0, v144, s[26:27]
	v_mfma_f32_16x16x32_f16 v[34:37], v[106:109], v[138:141], v[34:37]
	v_cndmask_b32_e64 v214, 0, v145, s[30:31]
	v_cvt_pk_f16_f32 v145, v217, v218
	v_cvt_pk_f16_f32 v144, v215, v216
	v_mfma_f32_16x16x32_f16 v[138:141], v[90:93], v[58:61], 0
	v_cvt_pk_f16_f32 v143, v213, v214
	v_cvt_pk_f16_f32 v142, v211, v212
	v_mfma_f32_16x16x32_f16 v[150:153], v[98:101], v[62:65], v[138:141]
	v_mfma_f32_16x16x32_f16 v[138:141], v[94:97], v[58:61], 0
	v_mfma_f32_16x16x32_f16 v[146:149], v[102:105], v[62:65], v[138:141]
	s_nop 5
	v_max_f32_e32 v154, 0xf149f2ca, v150
	v_cndmask_b32_e64 v154, v172, v154, s[6:7]
	v_max_f32_e32 v155, v154, v151
	v_cndmask_b32_e64 v154, v154, v155, s[8:9]
	v_max_f32_e32 v155, v154, v152
	v_cndmask_b32_e64 v154, v154, v155, s[10:11]
	v_max_f32_e32 v155, v154, v153
	v_cndmask_b32_e64 v154, v154, v155, s[14:15]
	v_max_f32_e32 v155, v154, v146
	v_cndmask_b32_e64 v154, v154, v155, s[12:13]
	v_max_f32_e32 v156, v147, v147
	v_mfma_f32_16x16x32_f16 v[138:141], v[86:89], v[58:61], 0
	v_max_f32_e32 v155, v154, v156
	v_cndmask_b32_e64 v154, v154, v155, s[16:17]
	v_max_f32_e32 v156, v148, v148
	v_max_f32_e32 v155, v154, v156
	v_mfma_f32_16x16x32_f16 v[46:49], v[134:137], v[142:145], v[46:49]
	v_cndmask_b32_e64 v154, v154, v155, s[18:19]
	v_max_f32_e32 v156, v149, v149
	v_mfma_f32_16x16x32_f16 v[42:45], v[126:129], v[142:145], v[42:45]
	v_max_f32_e32 v155, v154, v156
	v_cndmask_b32_e64 v154, v154, v155, s[22:23]
	v_mfma_f32_16x16x32_f16 v[38:41], v[118:121], v[142:145], v[38:41]
	v_mfma_f32_16x16x32_f16 v[34:37], v[110:113], v[142:145], v[34:37]
	v_mfma_f32_16x16x32_f16 v[142:145], v[82:85], v[62:65], v[138:141]
	v_mfma_f32_16x16x32_f16 v[138:141], v[78:81], v[58:61], 0
	v_mfma_f32_16x16x32_f16 v[138:141], v[74:77], v[62:65], v[138:141]
	s_nop 5
	v_max_f32_e32 v156, v142, v142
	v_max_f32_e32 v155, v154, v156
	v_cndmask_b32_e64 v154, v154, v155, s[20:21]
	v_max_f32_e32 v156, v143, v143
	v_max_f32_e32 v155, v154, v156
	v_cndmask_b32_e64 v154, v154, v155, s[24:25]
	v_max_f32_e32 v156, v144, v144
	v_max_f32_e32 v155, v154, v156
	v_cndmask_b32_e64 v154, v154, v155, s[26:27]
	v_max_f32_e32 v156, v145, v145
	v_max_f32_e32 v155, v154, v156
	v_cndmask_b32_e64 v154, v154, v155, s[30:31]
	v_max_f32_e32 v156, v138, v138
	v_max_f32_e32 v155, v154, v156
	v_cndmask_b32_e64 v154, v154, v155, s[28:29]
	v_max_f32_e32 v156, v139, v139
	v_max_f32_e32 v155, v154, v156
	v_cndmask_b32_e64 v154, v154, v155, s[34:35]
	v_max_f32_e32 v156, v140, v140
	v_max_f32_e32 v155, v154, v156
	v_cndmask_b32_e64 v154, v154, v155, s[36:37]
	v_max_f32_e32 v156, v141, v141
	v_max_f32_e32 v155, v154, v156
	v_cndmask_b32_e64 v154, v154, v155, s[38:39]
	v_add_f32_e32 v155, 0x41400000, v159
	v_cmp_gt_f32_e32 vcc, v154, v155
	s_cbranch_vccz .LBB0_984
	ds_bpermute_b32 v155, v173, v154
	v_max_f32_e32 v154, v154, v154
	v_mov_b32_e32 v156, v158
	v_mov_b32_e32 v157, v159
	v_mov_b32_e32 v158, v160
	s_waitcnt lgkmcnt(0)
	v_max_f32_e32 v155, v155, v155
	v_max_f32_e32 v154, v154, v155
	ds_bpermute_b32 v155, v188, v154
	s_waitcnt lgkmcnt(0)
	v_max3_f32 v155, v159, v154, v155
	v_sub_f32_e32 v154, v159, v155
	v_exp_f32_e32 v154, v154
	v_mov_b32_e32 v157, v155
	v_mov_b32_e32 v159, v155
	v_mul_f32_e32 v189, v189, v154
	v_pk_mul_f32 v[32:33], v[32:33], v[154:155] op_sel_hi:[1,0]
	v_pk_mul_f32 v[30:31], v[30:31], v[154:155] op_sel_hi:[1,0]
	v_pk_mul_f32 v[28:29], v[28:29], v[154:155] op_sel_hi:[1,0]
	v_pk_mul_f32 v[26:27], v[26:27], v[154:155] op_sel_hi:[1,0]
	v_pk_mul_f32 v[24:25], v[24:25], v[154:155] op_sel_hi:[1,0]
	v_pk_mul_f32 v[22:23], v[22:23], v[154:155] op_sel_hi:[1,0]
	v_pk_mul_f32 v[20:21], v[20:21], v[154:155] op_sel_hi:[1,0]
	v_pk_mul_f32 v[18:19], v[18:19], v[154:155] op_sel_hi:[1,0]
	s_branch .LBB0_985

; #define MFMA16(a, b, c) __builtin_amdgcn_mfma_f32_16x16x32_f16((a), (b), (c), 0, 0, 0)
;     ...
;     for (int it = 0; it < nit; ++it) {
;         const int kbN = kbof((it + 1 < nit) ? it + 1 : it);
;         const int nbA = kbN >> 5, nbB = (nbA + 1 <= maxblk) ? nbA + 1 : maxblk;
;         const f32x4 z = {0.f, 0.f, 0.f, 0.f};
; #pragma unroll
;         for (int s_ = 0; s_ < NS; ++s_) {
;             f32x4 s[4];
; #pragma unroll
;             for (int t = 0; t < 4; ++t) { s[t] = MFMA16(ka[2 * t], qf[s_][0], z); s[t] = MFMA16(ka[2 * t + 1], qf[s_][1], s[t]); }
;             if (s_ == NS - 1) {
;                 const half_t* kpA = kf + (size_t)nbA * 2048; const half_t* kpB = kf + (size_t)nbB * 2048;
; #pragma unroll
;                 for (int i = 0; i < 4; ++i) { ka[i] = *(const half8*)(kpA + i * 512); ka[4 + i] = *(const half8*)(kpB + i * 512); }
;             }
;             if (MODE != 1) {
;                 float mx = -1e30f;
; #pragma unroll
;                 for (int t = 0; t < 4; ++t)
; #pragma unroll
;                     for (int r = 0; r < 4; ++r) { if (valid(s_, kbA + 16 * t + 4 * g + r)) mx = fmaxf(mx, s[t][r]); }
;                 if (__ballot(mx > m[s_] + RESC_THR) != 0ull) {
;                     mx = fmaxf(mx, shx(mx, 16)); mx = fmaxf(mx, shx(mx, 32));
;                     const float mn = fmaxf(m[s_], mx); const float corr = __builtin_amdgcn_exp2f(m[s_] - mn); m[s_] = mn; l[s_] = l[s_] * corr;
;                     if (PV) {
; #pragma unroll
;                         for (int dt = 0; dt < 4; ++dt) o[s_][dt] = o[s_][dt] * corr;
;                     }
;                 }
;             }
;             float p[4][4]; float ps = 0.f;
; #pragma unroll
;             for (int t = 0; t < 4; ++t)
; #pragma unroll
;                 for (int r = 0; r < 4; ++r) { p[t][r] = valid(s_, kbA + 16 * t + 4 * g + r) ? __builtin_amdgcn_exp2f(s[t][r] - m[s_]) : 0.f; if (MODE == 1) p[t][r] *= l[s_]; ps += p[t][r]; }
;             if (MODE != 1) l[s_] = l[s_] + ps;
;             if (PV) {
;                 const half8 pfA = {(half_t)p[0][0], (half_t)p[0][1], (half_t)p[0][2], (half_t)p[0][3], (half_t)p[1][0], (half_t)p[1][1], (half_t)p[1][2], (half_t)p[1][3]};
;                 const half8 pfB = {(half_t)p[2][0], (half_t)p[2][1], (half_t)p[2][2], (half_t)p[2][3], (half_t)p[3][0], (half_t)p[3][1], (half_t)p[3][2], (half_t)p[3][3]};
; #pragma unroll
.LBB0_985:
	v_sub_f32_e32 v150, v150, v159
	v_sub_f32_e32 v146, v146, v159
	v_exp_f32_e32 v150, v150
	v_exp_f32_e32 v146, v146
	v_sub_f32_e32 v138, v138, v159
	v_exp_f32_e32 v138, v138
	v_sub_f32_e32 v142, v142, v159
	v_cndmask_b32_e64 v219, 0, v150, s[6:7]
	v_sub_f32_e32 v150, v151, v159
	v_cndmask_b32_e64 v223, 0, v146, s[12:13]
	v_sub_f32_e32 v146, v147, v159
	v_exp_f32_e32 v142, v142
	v_exp_f32_e32 v150, v150
	v_exp_f32_e32 v146, v146
	v_cndmask_b32_e64 v231, 0, v138, s[28:29]
	v_sub_f32_e32 v138, v139, v159
	v_exp_f32_e32 v138, v138
	v_cndmask_b32_e64 v227, 0, v142, s[20:21]
	v_sub_f32_e32 v142, v143, v159
	v_cndmask_b32_e64 v220, 0, v150, s[8:9]
	v_sub_f32_e32 v150, v152, v159
	v_cndmask_b32_e64 v224, 0, v146, s[16:17]
	v_sub_f32_e32 v146, v148, v159
	v_exp_f32_e32 v142, v142
	v_exp_f32_e32 v150, v150
	v_exp_f32_e32 v146, v146
	v_cndmask_b32_e64 v232, 0, v138, s[34:35]
	v_sub_f32_e32 v138, v140, v159
	v_exp_f32_e32 v138, v138
	v_cndmask_b32_e64 v228, 0, v142, s[24:25]
	v_sub_f32_e32 v142, v144, v159
	v_cndmask_b32_e64 v221, 0, v150, s[10:11]
	v_sub_f32_e32 v150, v153, v159
	v_cndmask_b32_e64 v225, 0, v146, s[18:19]
	v_sub_f32_e32 v146, v149, v159
	v_exp_f32_e32 v142, v142
	v_exp_f32_e32 v150, v150
	v_exp_f32_e32 v146, v146
	v_cndmask_b32_e64 v233, 0, v138, s[36:37]
	v_sub_f32_e32 v138, v141, v159
	s_add_i32 s47, s45, 1
	v_exp_f32_e32 v138, v138
	s_cmp_lt_i32 s45, s43
	v_mfma_f32_16x16x32_f16 v[90:93], v[90:93], v[66:69], 0
	s_cselect_b32 s2, s47, s45
	v_cndmask_b32_e64 v229, 0, v142, s[26:27]
	v_sub_f32_e32 v142, v145, v159
	s_lshl_b32 s2, s2, 6
	v_cndmask_b32_e64 v222, 0, v150, s[14:15]
	v_cndmask_b32_e64 v226, 0, v146, s[22:23]
	v_exp_f32_e32 v142, v142
	s_add_i32 s46, s2, s44
	v_cndmask_b32_e64 v159, 0, v138, s[38:39]
	v_cvt_pk_f16_f32 v141, v225, v226
	v_cvt_pk_f16_f32 v140, v223, v224
	v_cvt_pk_f16_f32 v139, v221, v222
	v_cvt_pk_f16_f32 v138, v219, v220
	s_lshr_b32 s84, s46, 5
	v_mfma_f32_16x16x32_f16 v[150:153], v[98:101], v[70:73], v[90:93]
	s_min_u32 s33, s84, 0x1fe
	s_lshl_b64 s[2:3], s[84:85], 12
	s_lshl_b32 s33, s33, 12
	v_mfma_f32_16x16x32_f16 v[30:33], v[130:133], v[138:141], v[30:33]
	v_cndmask_b32_e64 v230, 0, v142, s[30:31]
	v_lshl_add_u64 v[160:161], v[184:185], 0, s[2:3]
	s_add_i32 s84, s33, 0x1000
	v_mfma_f32_16x16x32_f16 v[26:29], v[122:125], v[138:141], v[26:29]
	v_cvt_pk_f16_f32 v145, v233, v159
	v_cvt_pk_f16_f32 v144, v231, v232
	v_cvt_pk_f16_f32 v143, v229, v230
	v_mfma_f32_16x16x32_f16 v[22:25], v[114:117], v[138:141], v[22:25]
	v_cvt_pk_f16_f32 v142, v227, v228
	v_lshl_add_u64 v[154:155], v[184:185], 0, s[84:85]
	v_mfma_f32_16x16x32_f16 v[18:21], v[106:109], v[138:141], v[18:21]
	v_mfma_f32_16x16x32_f16 v[90:93], v[94:97], v[66:69], 0
	v_mfma_f32_16x16x32_f16 v[86:89], v[86:89], v[66:69], 0
	v_mfma_f32_16x16x32_f16 v[78:81], v[78:81], v[66:69], 0
	v_mfma_f32_16x16x32_f16 v[30:33], v[134:137], v[142:145], v[30:33]
	v_mfma_f32_16x16x32_f16 v[26:29], v[126:129], v[142:145], v[26:29]
	v_mfma_f32_16x16x32_f16 v[22:25], v[118:121], v[142:145], v[22:25]
	v_mfma_f32_16x16x32_f16 v[18:21], v[110:113], v[142:145], v[18:21]
	v_mfma_f32_16x16x32_f16 v[138:141], v[102:105], v[70:73], v[90:93]
	v_mfma_f32_16x16x32_f16 v[142:145], v[82:85], v[70:73], v[86:89]
	v_mfma_f32_16x16x32_f16 v[146:149], v[74:77], v[70:73], v[78:81]
	s_nop 0
	flat_load_dwordx4 v[90:93], v[160:161]
	flat_load_dwordx4 v[86:89], v[154:155]
	flat_load_dwordx4 v[98:101], v[160:161] offset:1024
	flat_load_dwordx4 v[82:85], v[154:155] offset:1024
	flat_load_dwordx4 v[94:97], v[160:161] offset:2048
	flat_load_dwordx4 v[78:81], v[154:155] offset:2048
	flat_load_dwordx4 v[102:105], v[160:161] offset:3072
	flat_load_dwordx4 v[74:77], v[154:155] offset:3072
	v_max_f32_e32 v154, 0xf149f2ca, v150
	v_cndmask_b32_e64 v154, v172, v154, s[6:7]
	v_max_f32_e32 v155, v154, v151
	v_cndmask_b32_e64 v154, v154, v155, s[8:9]
	v_max_f32_e32 v155, v154, v152
	v_cndmask_b32_e64 v154, v154, v155, s[10:11]
	v_max_f32_e32 v155, v154, v153
	v_cndmask_b32_e64 v154, v154, v155, s[14:15]
	v_max_f32_e32 v155, v154, v138
	v_cndmask_b32_e64 v154, v154, v155, s[12:13]
	v_max_f32_e32 v160, v139, v139
	v_max_f32_e32 v155, v154, v160
	v_cndmask_b32_e64 v154, v154, v155, s[16:17]
	v_max_f32_e32 v160, v140, v140
	v_max_f32_e32 v155, v154, v160
	v_cndmask_b32_e64 v154, v154, v155, s[18:19]
	v_max_f32_e32 v160, v141, v141
	v_max_f32_e32 v155, v154, v160
	v_cndmask_b32_e64 v154, v154, v155, s[22:23]
	v_max_f32_e32 v160, v142, v142
	v_max_f32_e32 v155, v154, v160
	v_cndmask_b32_e64 v154, v154, v155, s[20:21]
	v_max_f32_e32 v160, v143, v143
	v_max_f32_e32 v155, v154, v160
	v_cndmask_b32_e64 v154, v154, v155, s[24:25]
	v_max_f32_e32 v160, v144, v144
	v_max_f32_e32 v155, v154, v160
	v_cndmask_b32_e64 v154, v154, v155, s[26:27]
	v_max_f32_e32 v160, v145, v145
	v_max_f32_e32 v155, v154, v160
	v_cndmask_b32_e64 v154, v154, v155, s[30:31]
	v_max_f32_e32 v160, v146, v146
	v_max_f32_e32 v155, v154, v160
	v_cndmask_b32_e64 v154, v154, v155, s[28:29]
	v_max_f32_e32 v160, v147, v147
	v_max_f32_e32 v155, v154, v160
	v_cndmask_b32_e64 v154, v154, v155, s[34:35]
	v_max_f32_e32 v160, v148, v148
	v_max_f32_e32 v155, v154, v160
	v_cndmask_b32_e64 v154, v154, v155, s[36:37]
	v_max_f32_e32 v160, v149, v149
	v_max_f32_e32 v155, v154, v160
	v_cndmask_b32_e64 v154, v154, v155, s[38:39]
	v_add_f32_e32 v155, 0x41400000, v158
	v_cmp_gt_f32_e32 vcc, v154, v155
	s_cbranch_vccz .LBB0_987
	ds_bpermute_b32 v155, v173, v154
	v_max_f32_e32 v154, v154, v154
	s_waitcnt lgkmcnt(0)
	v_max_f32_e32 v155, v155, v155
	v_max_f32_e32 v154, v154, v155
	ds_bpermute_b32 v155, v188, v154
	s_waitcnt lgkmcnt(0)
	v_max3_f32 v161, v158, v154, v155
	v_sub_f32_e32 v154, v158, v161
	v_exp_f32_e32 v160, v154
	v_mov_b32_e32 v154, v156
	v_mov_b32_e32 v155, v157
	v_mov_b32_e32 v156, v158
	v_mov_b32_e32 v156, v161
	v_mul_f32_e32 v163, v163, v160
	v_pk_mul_f32 v[16:17], v[16:17], v[160:161] op_sel_hi:[1,0]
	v_pk_mul_f32 v[14:15], v[14:15], v[160:161] op_sel_hi:[1,0]
	v_pk_mul_f32 v[12:13], v[12:13], v[160:161] op_sel_hi:[1,0]
	v_pk_mul_f32 v[10:11], v[10:11], v[160:161] op_sel_hi:[1,0]
	v_pk_mul_f32 v[8:9], v[8:9], v[160:161] op_sel_hi:[1,0]
	v_pk_mul_f32 v[6:7], v[6:7], v[160:161] op_sel_hi:[1,0]
	v_pk_mul_f32 v[4:5], v[4:5], v[160:161] op_sel_hi:[1,0]
	v_pk_mul_f32 v[2:3], v[2:3], v[160:161] op_sel_hi:[1,0]
	v_mov_b32_e32 v158, v161
	s_branch .LBB0_988

; #define MFMA16(a, b, c) __builtin_amdgcn_mfma_f32_16x16x32_f16((a), (b), (c), 0, 0, 0)
; __device__ __forceinline__ float shx(float v, int m) { return __shfl_xor(v, m); }
;     ...
;         for (int s_ = 0; s_ < NS; ++s_) {
;             f32x4 s[4];
; #pragma unroll
;             for (int t = 0; t < 4; ++t) { s[t] = MFMA16(ka[2 * t], qf[s_][0], z); s[t] = MFMA16(ka[2 * t + 1], qf[s_][1], s[t]); }
;             if (s_ == NS - 1) {
;                 const half_t* kpA = kf + (size_t)nbA * 2048; const half_t* kpB = kf + (size_t)nbB * 2048;
; #pragma unroll
;                 for (int i = 0; i < 4; ++i) { ka[i] = *(const half8*)(kpA + i * 512); ka[4 + i] = *(const half8*)(kpB + i * 512); }
;             }
;             if (MODE != 1) {
;                 float mx = -1e30f;
; #pragma unroll
;                 for (int t = 0; t < 4; ++t)
; #pragma unroll
;                     for (int r = 0; r < 4; ++r) { if (valid(s_, kbA + 16 * t + 4 * g + r)) mx = fmaxf(mx, s[t][r]); }
;                 if (__ballot(mx > m[s_] + RESC_THR) != 0ull) {
;                     mx = fmaxf(mx, shx(mx, 16)); mx = fmaxf(mx, shx(mx, 32));
;                     const float mn = fmaxf(m[s_], mx); const float corr = __builtin_amdgcn_exp2f(m[s_] - mn); m[s_] = mn; l[s_] = l[s_] * corr;
;                     if (PV) {
; #pragma unroll
;                         for (int dt = 0; dt < 4; ++dt) o[s_][dt] = o[s_][dt] * corr;
;                     }
;                 }
;             }
.LBB0_1008:
	global_load_dwordx4 v[132:135], v[108:109], off
	global_load_dwordx4 v[124:127], v[108:109], off offset:1024
	global_load_dwordx4 v[116:119], v[108:109], off offset:2048
	s_nop 0
	global_load_dwordx4 v[108:111], v[108:109], off offset:3072
	s_nop 0
	global_load_dwordx4 v[136:139], v[112:113], off
	global_load_dwordx4 v[128:131], v[112:113], off offset:1024
	global_load_dwordx4 v[120:123], v[112:113], off offset:2048
	s_nop 0
	global_load_dwordx4 v[112:115], v[112:113], off offset:3072
	s_waitcnt vmcnt(8) lgkmcnt(0)
	v_mfma_f32_16x16x32_f16 v[140:143], v[104:107], v[52:55], 0
	v_add_u32_e32 v2, s46, v166
	v_cmp_le_i32_e32 vcc, v2, v183
	v_cmp_gt_i32_e64 s[6:7], v2, v190
	v_mfma_f32_16x16x32_f16 v[148:151], v[96:99], v[56:59], v[140:143]
	s_and_b64 s[6:7], vcc, s[6:7]
	v_sub_u32_e32 v159, v2, v183
	s_movk_i32 s2, 0xff7f
	v_cmp_lt_i32_e32 vcc, v2, v183
	v_cmp_lt_i32_e64 s[8:9], s2, v159
	s_nop 2
	v_max_f32_e32 v3, 0xf149f2ca, v148
	v_cndmask_b32_e64 v3, v172, v3, s[6:7]
	v_mfma_f32_16x16x32_f16 v[140:143], v[100:103], v[52:55], 0
	s_and_b64 s[8:9], vcc, s[8:9]
	v_max_f32_e32 v159, v3, v149
	v_cndmask_b32_e64 v3, v3, v159, s[8:9]
	v_add_u32_e32 v159, 2, v2
	v_cmp_le_i32_e32 vcc, v159, v183
	v_cmp_gt_i32_e64 s[10:11], v159, v190
	s_and_b64 s[10:11], vcc, s[10:11]
	v_max_f32_e32 v159, v3, v150
	v_mfma_f32_16x16x32_f16 v[152:155], v[92:95], v[56:59], v[140:143]
	v_cndmask_b32_e64 v3, v3, v159, s[10:11]
	v_add_u32_e32 v159, 3, v2
	v_cmp_le_i32_e32 vcc, v159, v183
	v_cmp_gt_i32_e64 s[12:13], v159, v190
	s_and_b64 s[14:15], vcc, s[12:13]
	v_max_f32_e32 v159, v3, v151
	v_cndmask_b32_e64 v3, v3, v159, s[14:15]
	v_add_u32_e32 v159, 16, v2
	v_cmp_le_i32_e32 vcc, v159, v183
	v_cmp_gt_i32_e64 s[12:13], v159, v190
	s_and_b64 s[12:13], vcc, s[12:13]
	v_max_f32_e32 v159, v3, v152
	v_cndmask_b32_e64 v3, v3, v159, s[12:13]
	v_add_u32_e32 v159, 17, v2
	v_cmp_le_i32_e32 vcc, v159, v183
	v_cmp_gt_i32_e64 s[16:17], v159, v190
	v_max_f32_e32 v160, v153, v153
	v_mfma_f32_16x16x32_f16 v[140:143], v[88:91], v[52:55], 0
	s_and_b64 s[16:17], vcc, s[16:17]
	v_max_f32_e32 v159, v3, v160
	v_cndmask_b32_e64 v3, v3, v159, s[16:17]
	v_add_u32_e32 v159, 18, v2
	v_cmp_le_i32_e32 vcc, v159, v183
	v_cmp_gt_i32_e64 s[18:19], v159, v190
	v_max_f32_e32 v160, v154, v154
	s_and_b64 s[18:19], vcc, s[18:19]
	v_max_f32_e32 v159, v3, v160
	v_mfma_f32_16x16x32_f16 v[144:147], v[84:87], v[56:59], v[140:143]
	v_cndmask_b32_e64 v3, v3, v159, s[18:19]
	v_add_u32_e32 v159, 19, v2
	v_cmp_le_i32_e32 vcc, v159, v183
	v_cmp_gt_i32_e64 s[20:21], v159, v190
	v_max_f32_e32 v160, v155, v155
	s_and_b64 s[22:23], vcc, s[20:21]
	v_max_f32_e32 v159, v3, v160
	v_cndmask_b32_e64 v3, v3, v159, s[22:23]
	v_add_u32_e32 v159, 32, v2
	v_cmp_le_i32_e32 vcc, v159, v183
	v_cmp_gt_i32_e64 s[20:21], v159, v190
	v_max_f32_e32 v160, v144, v144
	s_and_b64 s[20:21], vcc, s[20:21]
	v_max_f32_e32 v159, v3, v160
	v_cndmask_b32_e64 v3, v3, v159, s[20:21]
	v_add_u32_e32 v159, 33, v2
	v_cmp_le_i32_e32 vcc, v159, v183
	v_cmp_gt_i32_e64 s[24:25], v159, v190
	v_max_f32_e32 v160, v145, v145
	v_mfma_f32_16x16x32_f16 v[140:143], v[80:83], v[52:55], 0
	s_and_b64 s[24:25], vcc, s[24:25]
	v_max_f32_e32 v159, v3, v160
	v_cndmask_b32_e64 v3, v3, v159, s[24:25]
	v_add_u32_e32 v159, 34, v2
	v_cmp_le_i32_e32 vcc, v159, v183
	v_cmp_gt_i32_e64 s[26:27], v159, v190
	v_max_f32_e32 v160, v146, v146
	s_and_b64 s[26:27], vcc, s[26:27]
	v_max_f32_e32 v159, v3, v160
	v_mfma_f32_16x16x32_f16 v[140:143], v[76:79], v[56:59], v[140:143]
	v_cndmask_b32_e64 v3, v3, v159, s[26:27]
	v_add_u32_e32 v159, 35, v2
	v_cmp_le_i32_e32 vcc, v159, v183
	v_cmp_gt_i32_e64 s[28:29], v159, v190
	v_max_f32_e32 v160, v147, v147
	s_and_b64 s[30:31], vcc, s[28:29]
	v_max_f32_e32 v159, v3, v160
	v_cndmask_b32_e64 v3, v3, v159, s[30:31]
	v_add_u32_e32 v159, 48, v2
	v_cmp_le_i32_e32 vcc, v159, v183
	v_cmp_gt_i32_e64 s[28:29], v159, v190
	v_max_f32_e32 v160, v140, v140
	s_and_b64 s[28:29], vcc, s[28:29]
	v_max_f32_e32 v159, v3, v160
	v_cndmask_b32_e64 v3, v3, v159, s[28:29]
	v_add_u32_e32 v159, 49, v2
	v_cmp_le_i32_e32 vcc, v159, v183
	v_cmp_gt_i32_e64 s[34:35], v159, v190
	v_max_f32_e32 v160, v141, v141
	s_and_b64 s[34:35], vcc, s[34:35]
	v_max_f32_e32 v159, v3, v160
	v_cndmask_b32_e64 v3, v3, v159, s[34:35]
	v_add_u32_e32 v159, 50, v2
	v_cmp_le_i32_e32 vcc, v159, v183
	v_cmp_gt_i32_e64 s[36:37], v159, v190
	v_max_f32_e32 v160, v142, v142
	s_and_b64 s[36:37], vcc, s[36:37]
	v_max_f32_e32 v159, v3, v160
	v_cndmask_b32_e64 v3, v3, v159, s[36:37]
	v_add_u32_e32 v2, 51, v2
	v_cmp_le_i32_e32 vcc, v2, v183
	v_cmp_gt_i32_e64 s[38:39], v2, v190
	v_max_f32_e32 v159, v143, v143
	s_and_b64 s[38:39], vcc, s[38:39]
	v_max_f32_e32 v2, v3, v159
	v_cndmask_b32_e64 v2, v3, v2, s[38:39]
	v_add_f32_e32 v3, 0x41400000, v156
	v_cmp_gt_f32_e32 vcc, v2, v3
	s_cbranch_vccz .LBB0_1010
	v_and_b32_e32 v159, 64, v204
	v_xor_b32_e32 v3, 16, v204
	v_add_u32_e32 v159, 64, v159
	v_cmp_lt_i32_e32 vcc, v3, v159
	v_xor_b32_e32 v160, 32, v204
	s_nop 0
	v_cndmask_b32_e32 v3, v204, v3, vcc
	v_lshlrev_b32_e32 v3, 2, v3
	ds_bpermute_b32 v3, v3, v2
	v_max_f32_e32 v2, v2, v2
	v_cmp_lt_i32_e32 vcc, v160, v159
	s_waitcnt lgkmcnt(0)
	v_max_f32_e32 v3, v3, v3
	v_max_f32_e32 v2, v2, v3
	v_cndmask_b32_e32 v3, v204, v160, vcc
	v_lshlrev_b32_e32 v3, 2, v3
	ds_bpermute_b32 v3, v3, v2
	v_mov_b32_e32 v162, v158
	v_mov_b32_e32 v160, v156
	v_mov_b32_e32 v161, v157
	s_waitcnt lgkmcnt(0)
	v_max3_f32 v3, v156, v2, v3
	v_sub_f32_e32 v2, v156, v3
	v_exp_f32_e32 v2, v2
	v_mov_b32_e32 v160, v3
	v_mov_b32_e32 v156, v3
	v_mul_f32_e32 v0, v0, v2
	v_pk_mul_f32 v[50:51], v[50:51], v[2:3] op_sel_hi:[1,0]
	v_pk_mul_f32 v[48:49], v[48:49], v[2:3] op_sel_hi:[1,0]
	v_pk_mul_f32 v[46:47], v[46:47], v[2:3] op_sel_hi:[1,0]
	v_pk_mul_f32 v[44:45], v[44:45], v[2:3] op_sel_hi:[1,0]
	v_pk_mul_f32 v[42:43], v[42:43], v[2:3] op_sel_hi:[1,0]
	v_pk_mul_f32 v[40:41], v[40:41], v[2:3] op_sel_hi:[1,0]
	v_pk_mul_f32 v[38:39], v[38:39], v[2:3] op_sel_hi:[1,0]
	v_pk_mul_f32 v[36:37], v[36:37], v[2:3] op_sel_hi:[1,0]
	s_branch .LBB0_1011

; #define MFMA16(a, b, c) __builtin_amdgcn_mfma_f32_16x16x32_f16((a), (b), (c), 0, 0, 0)
; __device__ __forceinline__ float shx(float v, int m) { return __shfl_xor(v, m); }
;     ...
;         for (int s_ = 0; s_ < NS; ++s_) {
;             f32x4 s[4];
; #pragma unroll
;             for (int t = 0; t < 4; ++t) { s[t] = MFMA16(ka[2 * t], qf[s_][0], z); s[t] = MFMA16(ka[2 * t + 1], qf[s_][1], s[t]); }
;             if (s_ == NS - 1) {
;                 const half_t* kpA = kf + (size_t)nbA * 2048; const half_t* kpB = kf + (size_t)nbB * 2048;
; #pragma unroll
;                 for (int i = 0; i < 4; ++i) { ka[i] = *(const half8*)(kpA + i * 512); ka[4 + i] = *(const half8*)(kpB + i * 512); }
;             }
;             if (MODE != 1) {
;                 float mx = -1e30f;
; #pragma unroll
;                 for (int t = 0; t < 4; ++t)
; #pragma unroll
;                     for (int r = 0; r < 4; ++r) { if (valid(s_, kbA + 16 * t + 4 * g + r)) mx = fmaxf(mx, s[t][r]); }
;                 if (__ballot(mx > m[s_] + RESC_THR) != 0ull) {
;                     mx = fmaxf(mx, shx(mx, 16)); mx = fmaxf(mx, shx(mx, 32));
;                     const float mn = fmaxf(m[s_], mx); const float corr = __builtin_amdgcn_exp2f(m[s_] - mn); m[s_] = mn; l[s_] = l[s_] * corr;
;                     if (PV) {
; #pragma unroll
;                         for (int dt = 0; dt < 4; ++dt) o[s_][dt] = o[s_][dt] * corr;
;                     }
;                 }
;             }
;             float p[4][4]; float ps = 0.f;
; #pragma unroll
;             for (int t = 0; t < 4; ++t)
; #pragma unroll
;                 for (int r = 0; r < 4; ++r) { p[t][r] = valid(s_, kbA + 16 * t + 4 * g + r) ? __builtin_amdgcn_exp2f(s[t][r] - m[s_]) : 0.f; if (MODE == 1) p[t][r] *= l[s_]; ps += p[t][r]; }
;             if (MODE != 1) l[s_] = l[s_] + ps;
;             if (PV) {
;                 const half8 pfA = {(half_t)p[0][0], (half_t)p[0][1], (half_t)p[0][2], (half_t)p[0][3], (half_t)p[1][0], (half_t)p[1][1], (half_t)p[1][2], (half_t)p[1][3]};
;                 const half8 pfB = {(half_t)p[2][0], (half_t)p[2][1], (half_t)p[2][2], (half_t)p[2][3], (half_t)p[3][0], (half_t)p[3][1], (half_t)p[3][2], (half_t)p[3][3]};
; #pragma unroll
;                 for (int dt = 0; dt < 4; ++dt) { o[s_][dt] = MFMA16(va[dt], pfA, o[s_][dt]); o[s_][dt] = MFMA16(va[4 + dt], pfB, o[s_][dt]); }
.LBB0_1011:
	v_sub_f32_e32 v2, v148, v156
	v_sub_f32_e32 v3, v149, v156
	v_exp_f32_e32 v2, v2
	v_exp_f32_e32 v3, v3
	v_sub_f32_e32 v148, v150, v156
	v_sub_f32_e32 v149, v151, v156
	v_cndmask_b32_e64 v191, 0, v2, s[6:7]
	v_cndmask_b32_e64 v192, 0, v3, s[8:9]
	v_sub_f32_e32 v2, v152, v156
	v_sub_f32_e32 v3, v153, v156
	v_exp_f32_e32 v2, v2
	v_exp_f32_e32 v3, v3
	v_exp_f32_e32 v148, v148
	v_exp_f32_e32 v149, v149
	v_cndmask_b32_e64 v195, 0, v2, s[12:13]
	v_cndmask_b32_e64 v196, 0, v3, s[16:17]
	v_sub_f32_e32 v2, v144, v156
	v_sub_f32_e32 v3, v145, v156
	v_exp_f32_e32 v2, v2
	v_exp_f32_e32 v3, v3
	v_cndmask_b32_e64 v193, 0, v148, s[10:11]
	v_cndmask_b32_e64 v194, 0, v149, s[14:15]
	v_sub_f32_e32 v148, v154, v156
	v_sub_f32_e32 v149, v155, v156
	v_exp_f32_e32 v148, v148
	v_exp_f32_e32 v149, v149
	v_cndmask_b32_e64 v209, 0, v2, s[20:21]
	v_cndmask_b32_e64 v210, 0, v3, s[24:25]
	v_sub_f32_e32 v2, v140, v156
	v_sub_f32_e32 v3, v141, v156
	v_sub_f32_e32 v140, v142, v156
	v_sub_f32_e32 v141, v143, v156
	v_exp_f32_e32 v140, v140
	v_exp_f32_e32 v141, v141
	v_cndmask_b32_e64 v197, 0, v148, s[18:19]
	v_cndmask_b32_e64 v208, 0, v149, s[22:23]
	v_cndmask_b32_e64 v215, 0, v140, s[36:37]
	v_cndmask_b32_e64 v216, 0, v141, s[38:39]
	v_cvt_pk_f16_f32 v143, v197, v208
	v_cvt_pk_f16_f32 v142, v195, v196
	v_cvt_pk_f16_f32 v141, v193, v194
	v_cvt_pk_f16_f32 v140, v191, v192
	v_exp_f32_e32 v2, v2
	v_exp_f32_e32 v3, v3
	s_waitcnt vmcnt(0)
	v_mfma_f32_16x16x32_f16 v[48:51], v[132:135], v[140:143], v[48:51]
	v_sub_f32_e32 v144, v146, v156
	v_cndmask_b32_e64 v213, 0, v2, s[28:29]
	v_cndmask_b32_e64 v214, 0, v3, s[34:35]
	v_mfma_f32_16x16x32_f16 v[44:47], v[124:127], v[140:143], v[44:47]
	v_sub_f32_e32 v145, v147, v156
	v_exp_f32_e32 v144, v144
	v_exp_f32_e32 v145, v145
	v_mfma_f32_16x16x32_f16 v[40:43], v[116:119], v[140:143], v[40:43]
	v_cvt_pk_f16_f32 v147, v215, v216
	v_cndmask_b32_e64 v211, 0, v144, s[26:27]
	v_cndmask_b32_e64 v212, 0, v145, s[30:31]
	v_mfma_f32_16x16x32_f16 v[36:39], v[108:111], v[140:143], v[36:39]
	v_cvt_pk_f16_f32 v146, v213, v214
	v_cvt_pk_f16_f32 v145, v211, v212
	v_cvt_pk_f16_f32 v144, v209, v210
	v_mfma_f32_16x16x32_f16 v[140:143], v[104:107], v[60:63], 0
	v_mfma_f32_16x16x32_f16 v[152:155], v[96:99], v[64:67], v[140:143]
	v_mfma_f32_16x16x32_f16 v[140:143], v[100:103], v[60:63], 0
	v_mfma_f32_16x16x32_f16 v[148:151], v[92:95], v[64:67], v[140:143]
	s_nop 5
	v_max_f32_e32 v2, 0xf149f2ca, v152
	v_cndmask_b32_e64 v2, v172, v2, s[6:7]
	v_max_f32_e32 v3, v2, v153
	v_cndmask_b32_e64 v2, v2, v3, s[8:9]
	v_max_f32_e32 v3, v2, v154
	v_cndmask_b32_e64 v2, v2, v3, s[10:11]
	v_max_f32_e32 v3, v2, v155
	v_cndmask_b32_e64 v2, v2, v3, s[14:15]
	v_max_f32_e32 v3, v2, v148
	v_cndmask_b32_e64 v2, v2, v3, s[12:13]
	v_max_f32_e32 v156, v149, v149
	v_mfma_f32_16x16x32_f16 v[140:143], v[88:91], v[60:63], 0
	v_max_f32_e32 v3, v2, v156
	v_cndmask_b32_e64 v2, v2, v3, s[16:17]
	v_max_f32_e32 v156, v150, v150
	v_max_f32_e32 v3, v2, v156
	v_mfma_f32_16x16x32_f16 v[48:51], v[136:139], v[144:147], v[48:51]
	v_cndmask_b32_e64 v2, v2, v3, s[18:19]
	v_max_f32_e32 v156, v151, v151
	v_mfma_f32_16x16x32_f16 v[44:47], v[128:131], v[144:147], v[44:47]
	v_max_f32_e32 v3, v2, v156
	v_cndmask_b32_e64 v2, v2, v3, s[22:23]
	v_mfma_f32_16x16x32_f16 v[40:43], v[120:123], v[144:147], v[40:43]
	v_mfma_f32_16x16x32_f16 v[36:39], v[112:115], v[144:147], v[36:39]
	v_mfma_f32_16x16x32_f16 v[144:147], v[84:87], v[64:67], v[140:143]
	v_mfma_f32_16x16x32_f16 v[140:143], v[80:83], v[60:63], 0
	v_mfma_f32_16x16x32_f16 v[140:143], v[76:79], v[64:67], v[140:143]
	s_nop 5
	v_max_f32_e32 v156, v144, v144
	v_max_f32_e32 v3, v2, v156
	v_cndmask_b32_e64 v2, v2, v3, s[20:21]
	v_max_f32_e32 v156, v145, v145
	v_max_f32_e32 v3, v2, v156
	v_cndmask_b32_e64 v2, v2, v3, s[24:25]
	v_max_f32_e32 v156, v146, v146
	v_max_f32_e32 v3, v2, v156
	v_cndmask_b32_e64 v2, v2, v3, s[26:27]
	v_max_f32_e32 v156, v147, v147
	v_max_f32_e32 v3, v2, v156
	v_cndmask_b32_e64 v2, v2, v3, s[30:31]
	v_max_f32_e32 v156, v140, v140
	v_max_f32_e32 v3, v2, v156
	v_cndmask_b32_e64 v2, v2, v3, s[28:29]
	v_max_f32_e32 v156, v141, v141
	v_max_f32_e32 v3, v2, v156
	v_cndmask_b32_e64 v2, v2, v3, s[34:35]
	v_max_f32_e32 v156, v142, v142
	v_max_f32_e32 v3, v2, v156
	v_cndmask_b32_e64 v2, v2, v3, s[36:37]
	v_max_f32_e32 v156, v143, v143
	v_max_f32_e32 v3, v2, v156
	v_cndmask_b32_e64 v2, v2, v3, s[38:39]
	v_add_f32_e32 v3, 0x41400000, v161
	v_cmp_gt_f32_e32 vcc, v2, v3
	s_cbranch_vccz .LBB0_1013
	v_and_b32_e32 v156, 64, v204
	v_xor_b32_e32 v3, 16, v204
	v_add_u32_e32 v156, 64, v156
	v_cmp_lt_i32_e32 vcc, v3, v156
	v_xor_b32_e32 v157, 32, v204
	v_mov_b32_e32 v158, v160
	v_cndmask_b32_e32 v3, v204, v3, vcc
	v_lshlrev_b32_e32 v3, 2, v3
	ds_bpermute_b32 v3, v3, v2
	v_max_f32_e32 v2, v2, v2
	v_cmp_lt_i32_e32 vcc, v157, v156
	v_mov_b32_e32 v159, v161
	v_mov_b32_e32 v160, v162
	s_waitcnt lgkmcnt(0)
	v_max_f32_e32 v3, v3, v3
	v_max_f32_e32 v2, v2, v3
	v_cndmask_b32_e32 v3, v204, v157, vcc
	v_lshlrev_b32_e32 v3, 2, v3
	ds_bpermute_b32 v3, v3, v2
	s_waitcnt lgkmcnt(0)
	v_max3_f32 v3, v161, v2, v3
	v_sub_f32_e32 v2, v161, v3
	v_exp_f32_e32 v2, v2
	v_mov_b32_e32 v159, v3
	v_mov_b32_e32 v161, v3
	v_mul_f32_e32 v173, v173, v2
	v_pk_mul_f32 v[34:35], v[34:35], v[2:3] op_sel_hi:[1,0]
	v_pk_mul_f32 v[32:33], v[32:33], v[2:3] op_sel_hi:[1,0]
	v_pk_mul_f32 v[30:31], v[30:31], v[2:3] op_sel_hi:[1,0]
	v_pk_mul_f32 v[28:29], v[28:29], v[2:3] op_sel_hi:[1,0]
	v_pk_mul_f32 v[26:27], v[26:27], v[2:3] op_sel_hi:[1,0]
	v_pk_mul_f32 v[24:25], v[24:25], v[2:3] op_sel_hi:[1,0]
	v_pk_mul_f32 v[22:23], v[22:23], v[2:3] op_sel_hi:[1,0]
	v_pk_mul_f32 v[20:21], v[20:21], v[2:3] op_sel_hi:[1,0]
	s_branch .LBB0_1014

; #define MFMA16(a, b, c) __builtin_amdgcn_mfma_f32_16x16x32_f16((a), (b), (c), 0, 0, 0)
;     ...
;     for (int it = 0; it < nit; ++it) {
;         const int kbN = kbof((it + 1 < nit) ? it + 1 : it);
;         const int nbA = kbN >> 5, nbB = (nbA + 1 <= maxblk) ? nbA + 1 : maxblk;
;         const f32x4 z = {0.f, 0.f, 0.f, 0.f};
; #pragma unroll
;         for (int s_ = 0; s_ < NS; ++s_) {
;             f32x4 s[4];
; #pragma unroll
;             for (int t = 0; t < 4; ++t) { s[t] = MFMA16(ka[2 * t], qf[s_][0], z); s[t] = MFMA16(ka[2 * t + 1], qf[s_][1], s[t]); }
;             if (s_ == NS - 1) {
;                 const half_t* kpA = kf + (size_t)nbA * 2048; const half_t* kpB = kf + (size_t)nbB * 2048;
; #pragma unroll
;                 for (int i = 0; i < 4; ++i) { ka[i] = *(const half8*)(kpA + i * 512); ka[4 + i] = *(const half8*)(kpB + i * 512); }
;             }
;             if (MODE != 1) {
;                 float mx = -1e30f;
; #pragma unroll
;                 for (int t = 0; t < 4; ++t)
; #pragma unroll
;                     for (int r = 0; r < 4; ++r) { if (valid(s_, kbA + 16 * t + 4 * g + r)) mx = fmaxf(mx, s[t][r]); }
;                 if (__ballot(mx > m[s_] + RESC_THR) != 0ull) {
;                     mx = fmaxf(mx, shx(mx, 16)); mx = fmaxf(mx, shx(mx, 32));
;                     const float mn = fmaxf(m[s_], mx); const float corr = __builtin_amdgcn_exp2f(m[s_] - mn); m[s_] = mn; l[s_] = l[s_] * corr;
;                     if (PV) {
; #pragma unroll
;                         for (int dt = 0; dt < 4; ++dt) o[s_][dt] = o[s_][dt] * corr;
;                     }
;                 }
;             }
;             float p[4][4]; float ps = 0.f;
; #pragma unroll
;             for (int t = 0; t < 4; ++t)
; #pragma unroll
;                 for (int r = 0; r < 4; ++r) { p[t][r] = valid(s_, kbA + 16 * t + 4 * g + r) ? __builtin_amdgcn_exp2f(s[t][r] - m[s_]) : 0.f; if (MODE == 1) p[t][r] *= l[s_]; ps += p[t][r]; }
;             if (MODE != 1) l[s_] = l[s_] + ps;
;             if (PV) {
;                 const half8 pfA = {(half_t)p[0][0], (half_t)p[0][1], (half_t)p[0][2], (half_t)p[0][3], (half_t)p[1][0], (half_t)p[1][1], (half_t)p[1][2], (half_t)p[1][3]};
;                 const half8 pfB = {(half_t)p[2][0], (half_t)p[2][1], (half_t)p[2][2], (half_t)p[2][3], (half_t)p[3][0], (half_t)p[3][1], (half_t)p[3][2], (half_t)p[3][3]};
; #pragma unroll
.LBB0_1014:
	v_sub_f32_e32 v152, v152, v161
	v_sub_f32_e32 v148, v148, v161
	v_exp_f32_e32 v152, v152
	v_exp_f32_e32 v148, v148
	v_sub_f32_e32 v140, v140, v161
	v_exp_f32_e32 v140, v140
	v_sub_f32_e32 v144, v144, v161
	v_cndmask_b32_e64 v162, 0, v152, s[6:7]
	v_sub_f32_e32 v152, v153, v161
	v_cndmask_b32_e64 v220, 0, v148, s[12:13]
	v_sub_f32_e32 v148, v149, v161
	v_exp_f32_e32 v144, v144
	v_exp_f32_e32 v152, v152
	v_exp_f32_e32 v148, v148
	v_cndmask_b32_e64 v228, 0, v140, s[28:29]
	v_sub_f32_e32 v140, v141, v161
	v_exp_f32_e32 v140, v140
	v_cndmask_b32_e64 v224, 0, v144, s[20:21]
	v_sub_f32_e32 v144, v145, v161
	v_cndmask_b32_e64 v217, 0, v152, s[8:9]
	v_sub_f32_e32 v152, v154, v161
	v_cndmask_b32_e64 v221, 0, v148, s[16:17]
	v_sub_f32_e32 v148, v150, v161
	v_exp_f32_e32 v144, v144
	v_exp_f32_e32 v152, v152
	v_exp_f32_e32 v148, v148
	v_cndmask_b32_e64 v229, 0, v140, s[34:35]
	v_sub_f32_e32 v140, v142, v161
	v_exp_f32_e32 v140, v140
	v_cndmask_b32_e64 v225, 0, v144, s[24:25]
	v_sub_f32_e32 v144, v146, v161
	v_cndmask_b32_e64 v218, 0, v152, s[10:11]
	v_sub_f32_e32 v152, v155, v161
	v_cndmask_b32_e64 v222, 0, v148, s[18:19]
	v_sub_f32_e32 v148, v151, v161
	v_exp_f32_e32 v144, v144
	v_exp_f32_e32 v152, v152
	v_exp_f32_e32 v148, v148
	v_cndmask_b32_e64 v230, 0, v140, s[36:37]
	v_sub_f32_e32 v140, v143, v161
	s_add_i32 s47, s45, 1
	v_exp_f32_e32 v140, v140
	s_cmp_lt_i32 s45, s43
	v_mfma_f32_16x16x32_f16 v[104:107], v[104:107], v[68:71], 0
	s_cselect_b32 s2, s47, s45
	v_cndmask_b32_e64 v226, 0, v144, s[26:27]
	v_sub_f32_e32 v144, v147, v161
	s_lshl_b32 s2, s2, 6
	v_cndmask_b32_e64 v219, 0, v152, s[14:15]
	v_cndmask_b32_e64 v223, 0, v148, s[22:23]
	v_exp_f32_e32 v144, v144
	s_add_i32 s46, s2, s44
	v_cndmask_b32_e64 v161, 0, v140, s[38:39]
	v_cvt_pk_f16_f32 v143, v222, v223
	v_cvt_pk_f16_f32 v142, v220, v221
	v_cvt_pk_f16_f32 v141, v218, v219
	v_cvt_pk_f16_f32 v140, v162, v217
	s_lshr_b32 s84, s46, 5
	v_mfma_f32_16x16x32_f16 v[152:155], v[96:99], v[72:75], v[104:107]
	s_min_u32 s33, s84, 0x1fe
	s_lshl_b64 s[2:3], s[84:85], 12
	s_lshl_b32 s33, s33, 12
	v_mfma_f32_16x16x32_f16 v[32:35], v[132:135], v[140:143], v[32:35]
	v_cndmask_b32_e64 v227, 0, v144, s[30:31]
	v_lshl_add_u64 v[156:157], v[186:187], 0, s[2:3]
	s_add_i32 s84, s33, 0x1000
	v_mfma_f32_16x16x32_f16 v[28:31], v[124:127], v[140:143], v[28:31]
	v_cvt_pk_f16_f32 v147, v230, v161
	v_cvt_pk_f16_f32 v146, v228, v229
	v_cvt_pk_f16_f32 v145, v226, v227
	v_mfma_f32_16x16x32_f16 v[24:27], v[116:119], v[140:143], v[24:27]
	v_cvt_pk_f16_f32 v144, v224, v225
	v_lshl_add_u64 v[2:3], v[186:187], 0, s[84:85]
	v_mfma_f32_16x16x32_f16 v[20:23], v[108:111], v[140:143], v[20:23]
	v_mfma_f32_16x16x32_f16 v[96:99], v[100:103], v[68:71], 0
	v_mfma_f32_16x16x32_f16 v[88:91], v[88:91], v[68:71], 0
	v_mfma_f32_16x16x32_f16 v[80:83], v[80:83], v[68:71], 0
	v_mfma_f32_16x16x32_f16 v[32:35], v[136:139], v[144:147], v[32:35]
	v_mfma_f32_16x16x32_f16 v[28:31], v[128:131], v[144:147], v[28:31]
	v_mfma_f32_16x16x32_f16 v[24:27], v[120:123], v[144:147], v[24:27]
	v_mfma_f32_16x16x32_f16 v[20:23], v[112:115], v[144:147], v[20:23]
	v_mfma_f32_16x16x32_f16 v[140:143], v[92:95], v[72:75], v[96:99]
	v_mfma_f32_16x16x32_f16 v[144:147], v[84:87], v[72:75], v[88:91]
	v_mfma_f32_16x16x32_f16 v[148:151], v[76:79], v[72:75], v[80:83]
	global_load_dwordx4 v[104:107], v[156:157], off
	s_nop 0
	global_load_dwordx4 v[88:91], v[2:3], off
	global_load_dwordx4 v[96:99], v[156:157], off offset:1024
	global_load_dwordx4 v[84:87], v[2:3], off offset:1024
	global_load_dwordx4 v[100:103], v[156:157], off offset:2048
	global_load_dwordx4 v[80:83], v[2:3], off offset:2048
	global_load_dwordx4 v[92:95], v[156:157], off offset:3072
	global_load_dwordx4 v[76:79], v[2:3], off offset:3072
	v_max_f32_e32 v2, 0xf149f2ca, v152
	v_cndmask_b32_e64 v2, v172, v2, s[6:7]
	v_max_f32_e32 v3, v2, v153
	v_cndmask_b32_e64 v2, v2, v3, s[8:9]
	v_max_f32_e32 v3, v2, v154
	v_cndmask_b32_e64 v2, v2, v3, s[10:11]
	v_max_f32_e32 v3, v2, v155
	v_cndmask_b32_e64 v2, v2, v3, s[14:15]
	v_max_f32_e32 v3, v2, v140
	v_cndmask_b32_e64 v2, v2, v3, s[12:13]
	v_max_f32_e32 v156, v141, v141
	v_max_f32_e32 v3, v2, v156
	v_cndmask_b32_e64 v2, v2, v3, s[16:17]
	v_max_f32_e32 v156, v142, v142
	v_max_f32_e32 v3, v2, v156
	v_cndmask_b32_e64 v2, v2, v3, s[18:19]
	v_max_f32_e32 v156, v143, v143
	v_max_f32_e32 v3, v2, v156
	v_cndmask_b32_e64 v2, v2, v3, s[22:23]
	v_max_f32_e32 v156, v144, v144
	v_max_f32_e32 v3, v2, v156
	v_cndmask_b32_e64 v2, v2, v3, s[20:21]
	v_max_f32_e32 v156, v145, v145
	v_max_f32_e32 v3, v2, v156
	v_cndmask_b32_e64 v2, v2, v3, s[24:25]
	v_max_f32_e32 v156, v146, v146
	v_max_f32_e32 v3, v2, v156
	v_cndmask_b32_e64 v2, v2, v3, s[26:27]
	v_max_f32_e32 v156, v147, v147
	v_max_f32_e32 v3, v2, v156
	v_cndmask_b32_e64 v2, v2, v3, s[30:31]
	v_max_f32_e32 v156, v148, v148
	v_max_f32_e32 v3, v2, v156
	v_cndmask_b32_e64 v2, v2, v3, s[28:29]
	v_max_f32_e32 v156, v149, v149
	v_max_f32_e32 v3, v2, v156
	v_cndmask_b32_e64 v2, v2, v3, s[34:35]
	v_max_f32_e32 v156, v150, v150
	v_max_f32_e32 v3, v2, v156
	v_cndmask_b32_e64 v2, v2, v3, s[36:37]
	v_max_f32_e32 v156, v151, v151
	v_max_f32_e32 v3, v2, v156
	v_cndmask_b32_e64 v2, v2, v3, s[38:39]
	v_add_f32_e32 v3, 0x41400000, v160
	v_cmp_gt_f32_e32 vcc, v2, v3
	s_cbranch_vccz .LBB0_1016
	v_and_b32_e32 v156, 64, v204
	v_xor_b32_e32 v3, 16, v204
	v_add_u32_e32 v156, 64, v156
	v_cmp_lt_i32_e32 vcc, v3, v156
	v_xor_b32_e32 v157, 32, v204
	s_nop 0
	v_cndmask_b32_e32 v3, v204, v3, vcc
	v_lshlrev_b32_e32 v3, 2, v3
	ds_bpermute_b32 v3, v3, v2
	v_max_f32_e32 v2, v2, v2
	v_cmp_lt_i32_e32 vcc, v157, v156
	s_waitcnt lgkmcnt(0)
	v_max_f32_e32 v3, v3, v3
	v_max_f32_e32 v2, v2, v3
	v_cndmask_b32_e32 v3, v204, v157, vcc
	v_lshlrev_b32_e32 v3, 2, v3
	ds_bpermute_b32 v3, v3, v2
	v_mov_b32_e32 v156, v158
	v_mov_b32_e32 v157, v159
	v_mov_b32_e32 v158, v160
	s_waitcnt lgkmcnt(0)
	v_max3_f32 v3, v160, v2, v3
	v_sub_f32_e32 v2, v160, v3
	v_exp_f32_e32 v2, v2
	v_mov_b32_e32 v158, v3
	v_mov_b32_e32 v160, v3
	v_mul_f32_e32 v167, v167, v2
	v_pk_mul_f32 v[18:19], v[18:19], v[2:3] op_sel_hi:[1,0]
	v_pk_mul_f32 v[16:17], v[16:17], v[2:3] op_sel_hi:[1,0]
	v_pk_mul_f32 v[14:15], v[14:15], v[2:3] op_sel_hi:[1,0]
	v_pk_mul_f32 v[12:13], v[12:13], v[2:3] op_sel_hi:[1,0]
	v_pk_mul_f32 v[10:11], v[10:11], v[2:3] op_sel_hi:[1,0]
	v_pk_mul_f32 v[8:9], v[8:9], v[2:3] op_sel_hi:[1,0]
	v_pk_mul_f32 v[6:7], v[6:7], v[2:3] op_sel_hi:[1,0]
	v_pk_mul_f32 v[4:5], v[4:5], v[2:3] op_sel_hi:[1,0]
	s_branch .LBB0_1017

; #define MFMA16(a, b, c) __builtin_amdgcn_mfma_f32_16x16x32_f16((a), (b), (c), 0, 0, 0)
; __device__ __forceinline__ float shx(float v, int m) { return __shfl_xor(v, m); }
;     ...
;         for (int s_ = 0; s_ < NS; ++s_) {
;             f32x4 s[4];
; #pragma unroll
;             for (int t = 0; t < 4; ++t) { s[t] = MFMA16(ka[2 * t], qf[s_][0], z); s[t] = MFMA16(ka[2 * t + 1], qf[s_][1], s[t]); }
;             if (s_ == NS - 1) {
;                 const half_t* kpA = kf + (size_t)nbA * 2048; const half_t* kpB = kf + (size_t)nbB * 2048;
; #pragma unroll
;                 for (int i = 0; i < 4; ++i) { ka[i] = *(const half8*)(kpA + i * 512); ka[4 + i] = *(const half8*)(kpB + i * 512); }
;             }
;             if (MODE != 1) {
;                 float mx = -1e30f;
; #pragma unroll
;                 for (int t = 0; t < 4; ++t)
; #pragma unroll
;                     for (int r = 0; r < 4; ++r) { if (valid(s_, kbA + 16 * t + 4 * g + r)) mx = fmaxf(mx, s[t][r]); }
;                 if (__ballot(mx > m[s_] + RESC_THR) != 0ull) {
;                     mx = fmaxf(mx, shx(mx, 16)); mx = fmaxf(mx, shx(mx, 32));
;                     const float mn = fmaxf(m[s_], mx); const float corr = __builtin_amdgcn_exp2f(m[s_] - mn); m[s_] = mn; l[s_] = l[s_] * corr;
;                     if (PV) {
; #pragma unroll
;                         for (int dt = 0; dt < 4; ++dt) o[s_][dt] = o[s_][dt] * corr;
;                     }
;                 }
;             }
.LBB0_1023:
	s_waitcnt vmcnt(0) lgkmcnt(0)
	v_mfma_f32_16x16x32_f16 v[86:89], v[78:81], v[34:37], 0
	flat_load_dwordx4 v[110:113], v[84:85]
	flat_load_dwordx4 v[102:105], v[84:85] offset:1024
	v_add_u32_e32 v147, s55, v166
	v_cmp_ge_i32_e32 vcc, v144, v147
	v_mfma_f32_16x16x32_f16 v[122:125], v[74:77], v[38:41], v[86:89]
	flat_load_dwordx4 v[94:97], v[84:85] offset:2048
	s_nop 1
	flat_load_dwordx4 v[86:89], v[84:85] offset:3072
	flat_load_dwordx4 v[106:109], v[82:83]
	flat_load_dwordx4 v[98:101], v[82:83] offset:1024
	flat_load_dwordx4 v[90:93], v[82:83] offset:2048
	s_nop 0
	flat_load_dwordx4 v[82:85], v[82:83] offset:3072
	v_cmp_gt_i32_e64 s[6:7], v147, v131
	v_mfma_f32_16x16x32_f16 v[114:117], v[70:73], v[34:37], 0
	s_and_b64 s[6:7], vcc, s[6:7]
	v_cmp_gt_i32_e32 vcc, v144, v147
	v_cmp_ge_i32_e64 s[8:9], v147, v131
	v_mfma_f32_16x16x32_f16 v[126:129], v[58:61], v[38:41], v[114:117]
	s_and_b64 s[8:9], vcc, s[8:9]
	v_add_u32_e32 v148, 2, v147
	v_cmp_le_i32_e32 vcc, v148, v144
	s_nop 0
	v_max_f32_e32 v114, v122, v122
	v_max_f32_e32 v118, 0xf149f2ca, v114
	v_mfma_f32_16x16x32_f16 v[114:117], v[66:69], v[34:37], 0
	v_cndmask_b32_e64 v142, v172, v118, s[6:7]
	v_cmp_gt_i32_e64 s[10:11], v148, v131
	s_and_b64 s[12:13], vcc, s[10:11]
	v_mfma_f32_16x16x32_f16 v[118:121], v[62:65], v[38:41], v[114:117]
	v_add_u32_e32 v149, 3, v147
	v_cmp_le_i32_e32 vcc, v149, v144
	v_cmp_gt_i32_e64 s[10:11], v149, v131
	s_nop 0
	v_max_f32_e32 v114, v123, v123
	v_max_f32_e32 v143, v142, v114
	v_cndmask_b32_e64 v142, v142, v143, s[8:9]
	v_max_f32_e32 v143, v142, v124
	v_cndmask_b32_e64 v142, v142, v143, s[12:13]
	v_max_f32_e32 v143, v142, v125
	s_and_b64 s[14:15], vcc, s[10:11]
	v_add_u32_e32 v152, 16, v147
	v_cndmask_b32_e64 v142, v142, v143, s[14:15]
	v_cmp_le_i32_e32 vcc, v152, v144
	v_cmp_gt_i32_e64 s[10:11], v152, v131
	v_max_f32_e32 v143, v142, v126
	s_and_b64 s[10:11], vcc, s[10:11]
	v_cndmask_b32_e64 v142, v142, v143, s[10:11]
	v_add_u32_e32 v150, 17, v147
	v_cmp_le_i32_e32 vcc, v150, v144
	v_cmp_gt_i32_e64 s[16:17], v150, v131
	v_max_f32_e32 v151, v127, v127
	v_max_f32_e32 v143, v142, v151
	s_and_b64 s[16:17], vcc, s[16:17]
	v_cndmask_b32_e64 v142, v142, v143, s[16:17]
	v_add_u32_e32 v151, 18, v147
	v_cmp_le_i32_e32 vcc, v151, v144
	v_cmp_gt_i32_e64 s[18:19], v151, v131
	v_max_f32_e32 v153, v128, v128
	v_max_f32_e32 v143, v142, v153
	s_and_b64 s[18:19], vcc, s[18:19]
	v_cndmask_b32_e64 v142, v142, v143, s[18:19]
	v_add_u32_e32 v153, 19, v147
	v_cmp_le_i32_e32 vcc, v153, v144
	v_cmp_gt_i32_e64 s[20:21], v153, v131
	v_max_f32_e32 v154, v129, v129
	v_max_f32_e32 v143, v142, v154
	s_and_b64 s[22:23], vcc, s[20:21]
	v_cndmask_b32_e64 v142, v142, v143, s[22:23]
	v_add_u32_e32 v154, 32, v147
	v_cmp_le_i32_e32 vcc, v154, v144
	v_cmp_gt_i32_e64 s[20:21], v154, v131
	v_max_f32_e32 v155, v118, v118
	v_max_f32_e32 v143, v142, v155
	s_and_b64 s[20:21], vcc, s[20:21]
	v_cndmask_b32_e64 v142, v142, v143, s[20:21]
	v_add_u32_e32 v155, 33, v147
	v_cmp_le_i32_e32 vcc, v155, v144
	v_cmp_gt_i32_e64 s[24:25], v155, v131
	v_max_f32_e32 v156, v119, v119
	v_mfma_f32_16x16x32_f16 v[114:117], v[54:57], v[34:37], 0
	v_max_f32_e32 v143, v142, v156
	s_and_b64 s[24:25], vcc, s[24:25]
	v_cndmask_b32_e64 v142, v142, v143, s[24:25]
	v_add_u32_e32 v156, 34, v147
	v_cmp_le_i32_e32 vcc, v156, v144
	v_cmp_gt_i32_e64 s[26:27], v156, v131
	v_max_f32_e32 v157, v120, v120
	v_max_f32_e32 v143, v142, v157
	s_and_b64 s[26:27], vcc, s[26:27]
	v_mfma_f32_16x16x32_f16 v[114:117], v[50:53], v[38:41], v[114:117]
	v_cndmask_b32_e64 v142, v142, v143, s[26:27]
	v_add_u32_e32 v157, 35, v147
	v_cmp_le_i32_e32 vcc, v157, v144
	v_cmp_gt_i32_e64 s[28:29], v157, v131
	v_max_f32_e32 v158, v121, v121
	v_max_f32_e32 v143, v142, v158
	s_and_b64 s[30:31], vcc, s[28:29]
	v_cndmask_b32_e64 v142, v142, v143, s[30:31]
	v_add_u32_e32 v158, 48, v147
	v_cmp_le_i32_e32 vcc, v158, v144
	v_cmp_gt_i32_e64 s[28:29], v158, v131
	v_max_f32_e32 v159, v114, v114
	v_max_f32_e32 v143, v142, v159
	s_and_b64 s[28:29], vcc, s[28:29]
	v_cndmask_b32_e64 v142, v142, v143, s[28:29]
	v_add_u32_e32 v159, 49, v147
	v_cmp_le_i32_e32 vcc, v159, v144
	v_cmp_gt_i32_e64 s[34:35], v159, v131
	v_max_f32_e32 v160, v115, v115
	v_max_f32_e32 v143, v142, v160
	s_and_b64 s[34:35], vcc, s[34:35]
	v_cndmask_b32_e64 v142, v142, v143, s[34:35]
	v_add_u32_e32 v160, 50, v147
	v_cmp_le_i32_e32 vcc, v160, v144
	v_cmp_gt_i32_e64 s[36:37], v160, v131
	v_max_f32_e32 v161, v116, v116
	v_max_f32_e32 v143, v142, v161
	s_and_b64 s[36:37], vcc, s[36:37]
	v_cndmask_b32_e64 v142, v142, v143, s[36:37]
	v_add_u32_e32 v161, 51, v147
	v_cmp_le_i32_e32 vcc, v161, v144
	v_cmp_gt_i32_e64 s[38:39], v161, v131
	v_max_f32_e32 v162, v117, v117
	v_max_f32_e32 v143, v142, v162
	s_and_b64 s[38:39], vcc, s[38:39]
	v_cndmask_b32_e64 v142, v142, v143, s[38:39]
	v_add_f32_e32 v143, 0x41400000, v136
	v_cmp_gt_f32_e32 vcc, v142, v143
	s_cbranch_vccz .LBB0_1025
	v_and_b32_e32 v162, 64, v204
	v_xor_b32_e32 v143, 16, v204
	v_add_u32_e32 v162, 64, v162
	v_cmp_lt_i32_e32 vcc, v143, v162
	s_nop 1
	v_cndmask_b32_e32 v143, v204, v143, vcc
	v_lshlrev_b32_e32 v143, 2, v143
	ds_bpermute_b32 v143, v143, v142
	v_max_f32_e32 v142, v142, v142
	s_waitcnt lgkmcnt(0)
	v_max_f32_e32 v143, v143, v143
	v_max_f32_e32 v142, v142, v143
	v_xor_b32_e32 v143, 32, v204
	v_cmp_lt_i32_e32 vcc, v143, v162
	s_nop 1
	v_cndmask_b32_e32 v143, v204, v143, vcc
	v_lshlrev_b32_e32 v143, 2, v143
	ds_bpermute_b32 v143, v143, v142
	s_waitcnt lgkmcnt(0)
	v_max3_f32 v142, v136, v142, v143
	v_sub_f32_e32 v136, v136, v142
	v_exp_f32_e32 v136, v136
	v_mov_b32_e32 v143, v137
	v_mul_f32_e32 v134, v134, v136
	v_pk_mul_f32 v[32:33], v[32:33], v[136:137] op_sel_hi:[1,0]
	v_pk_mul_f32 v[30:31], v[30:31], v[136:137] op_sel_hi:[1,0]
	v_pk_mul_f32 v[28:29], v[28:29], v[136:137] op_sel_hi:[1,0]
	v_pk_mul_f32 v[26:27], v[26:27], v[136:137] op_sel_hi:[1,0]
	v_pk_mul_f32 v[24:25], v[24:25], v[136:137] op_sel_hi:[1,0]
	v_pk_mul_f32 v[22:23], v[22:23], v[136:137] op_sel_hi:[1,0]
	v_pk_mul_f32 v[20:21], v[20:21], v[136:137] op_sel_hi:[1,0]
	v_pk_mul_f32 v[18:19], v[18:19], v[136:137] op_sel_hi:[1,0]
	v_mov_b32_e32 v136, v142
	s_branch .LBB0_1026

; #define MFMA16(a, b, c) __builtin_amdgcn_mfma_f32_16x16x32_f16((a), (b), (c), 0, 0, 0)
;     ...
;             float p[4][4]; float ps = 0.f;
; #pragma unroll
;             for (int t = 0; t < 4; ++t)
; #pragma unroll
;                 for (int r = 0; r < 4; ++r) { p[t][r] = valid(s_, kbA + 16 * t + 4 * g + r) ? __builtin_amdgcn_exp2f(s[t][r] - m[s_]) : 0.f; if (MODE == 1) p[t][r] *= l[s_]; ps += p[t][r]; }
;             if (MODE != 1) l[s_] = l[s_] + ps;
;             if (PV) {
;                 const half8 pfA = {(half_t)p[0][0], (half_t)p[0][1], (half_t)p[0][2], (half_t)p[0][3], (half_t)p[1][0], (half_t)p[1][1], (half_t)p[1][2], (half_t)p[1][3]};
;                 const half8 pfB = {(half_t)p[2][0], (half_t)p[2][1], (half_t)p[2][2], (half_t)p[2][3], (half_t)p[3][0], (half_t)p[3][1], (half_t)p[3][2], (half_t)p[3][3]};
; #pragma unroll
;                 for (int dt = 0; dt < 4; ++dt) { o[s_][dt] = MFMA16(va[dt], pfA, o[s_][dt]); o[s_][dt] = MFMA16(va[4 + dt], pfB, o[s_][dt]); }
.LBB0_1026:
	v_sub_f32_e32 v122, v122, v136
	v_exp_f32_e32 v122, v122
	v_sub_f32_e32 v123, v123, v136
	v_sub_f32_e32 v126, v126, v136
	v_sub_f32_e32 v127, v127, v136
	v_sub_f32_e32 v128, v128, v136
	v_sub_f32_e32 v129, v129, v136
	v_exp_f32_e32 v123, v123
	v_sub_f32_e32 v124, v124, v136
	v_exp_f32_e32 v126, v126
	v_exp_f32_e32 v127, v127
	v_exp_f32_e32 v128, v128
	v_exp_f32_e32 v129, v129
	v_mfma_f32_16x16x32_f16 v[78:81], v[78:81], v[42:45], 0
	v_exp_f32_e32 v124, v124
	v_sub_f32_e32 v125, v125, v136
	v_exp_f32_e32 v125, v125
	v_cndmask_b32_e64 v122, 0, v122, s[6:7]
	v_cndmask_b32_e64 v123, 0, v123, s[8:9]
	v_cndmask_b32_e64 v162, 0, v126, s[10:11]
	v_cndmask_b32_e64 v167, 0, v127, s[16:17]
	v_cndmask_b32_e64 v173, 0, v128, s[18:19]
	v_cndmask_b32_e64 v183, 0, v129, s[22:23]
	v_sub_f32_e32 v114, v114, v136
	v_sub_f32_e32 v115, v115, v136
	v_mfma_f32_16x16x32_f16 v[126:129], v[74:77], v[46:49], v[78:81]
	v_add_f32_e32 v74, 0, v122
	v_cndmask_b32_e64 v124, 0, v124, s[12:13]
	v_exp_f32_e32 v114, v114
	v_exp_f32_e32 v115, v115
	v_sub_f32_e32 v116, v116, v136
	v_sub_f32_e32 v117, v117, v136
	v_add_f32_e32 v74, v123, v74
	v_mfma_f32_16x16x32_f16 v[70:73], v[70:73], v[42:45], 0
	v_cndmask_b32_e64 v125, 0, v125, s[14:15]
	v_sub_f32_e32 v118, v118, v136
	v_exp_f32_e32 v116, v116
	v_exp_f32_e32 v117, v117
	v_add_f32_e32 v74, v124, v74
	v_exp_f32_e32 v118, v118
	v_sub_f32_e32 v119, v119, v136
	v_add_f32_e32 v74, v125, v74
	v_exp_f32_e32 v119, v119
	v_sub_f32_e32 v120, v120, v136
	v_sub_f32_e32 v121, v121, v136
	v_add_f32_e32 v74, v162, v74
	v_exp_f32_e32 v120, v120
	v_exp_f32_e32 v121, v121
	v_cndmask_b32_e64 v190, 0, v114, s[28:29]
	v_cndmask_b32_e64 v191, 0, v115, s[34:35]
	v_cvt_pk_f16_f32 v115, v124, v125
	v_cvt_pk_f16_f32 v114, v122, v123
	v_mfma_f32_16x16x32_f16 v[122:125], v[58:61], v[46:49], v[70:73]
	v_add_f32_e32 v58, v167, v74
	v_cndmask_b32_e64 v192, 0, v116, s[36:37]
	v_cndmask_b32_e64 v193, 0, v117, s[38:39]
	v_cvt_pk_f16_f32 v117, v173, v183
	v_cvt_pk_f16_f32 v116, v162, v167
	s_add_i32 s56, s54, 1
	v_add_f32_e32 v58, v173, v58
	v_cndmask_b32_e64 v186, 0, v118, s[20:21]
	s_waitcnt vmcnt(0) lgkmcnt(0)
; #define MFMA16(a, b, c) __builtin_amdgcn_mfma_f32_16x16x32_f16((a), (b), (c), 0, 0, 0)
; __device__ __forceinline__ float shx(float v, int m) { return __shfl_xor(v, m); }
;     ...
;         for (int s_ = 0; s_ < NS; ++s_) {
;             f32x4 s[4];
; #pragma unroll
;             for (int t = 0; t < 4; ++t) { s[t] = MFMA16(ka[2 * t], qf[s_][0], z); s[t] = MFMA16(ka[2 * t + 1], qf[s_][1], s[t]); }
;             if (s_ == NS - 1) {
;                 const half_t* kpA = kf + (size_t)nbA * 2048; const half_t* kpB = kf + (size_t)nbB * 2048;
; #pragma unroll
;                 for (int i = 0; i < 4; ++i) { ka[i] = *(const half8*)(kpA + i * 512); ka[4 + i] = *(const half8*)(kpB + i * 512); }
;             }
;             if (MODE != 1) {
;                 float mx = -1e30f;
; #pragma unroll
;                 for (int t = 0; t < 4; ++t)
; #pragma unroll
;                     for (int r = 0; r < 4; ++r) { if (valid(s_, kbA + 16 * t + 4 * g + r)) mx = fmaxf(mx, s[t][r]); }
;                 if (__ballot(mx > m[s_] + RESC_THR) != 0ull) {
;                     mx = fmaxf(mx, shx(mx, 16)); mx = fmaxf(mx, shx(mx, 32));
;                     const float mn = fmaxf(m[s_], mx); const float corr = __builtin_amdgcn_exp2f(m[s_] - mn); m[s_] = mn; l[s_] = l[s_] * corr;
;                     if (PV) {
; #pragma unroll
;                         for (int dt = 0; dt < 4; ++dt) o[s_][dt] = o[s_][dt] * corr;
;                     }
; __device__ __forceinline__ void b_unit(const ACtx& X, int b, int h6, int fb, int lane) {
;     ...
;     auto valid = [&](int s_, int kf) { return kf <= iqs[s_] && iqs[s_] - kf <= 128; };
	v_mfma_f32_16x16x32_f16 v[30:33], v[110:113], v[114:117], v[30:33]
	s_cmp_lt_i32 s54, s53
	v_add_f32_e32 v70, v183, v58
	v_cndmask_b32_e64 v187, 0, v119, s[24:25]
	v_mfma_f32_16x16x32_f16 v[26:29], v[102:105], v[114:117], v[26:29]
	s_cselect_b32 s2, s56, s54
	v_cndmask_b32_e64 v188, 0, v120, s[26:27]
	v_cndmask_b32_e64 v189, 0, v121, s[30:31]
	v_mfma_f32_16x16x32_f16 v[22:25], v[94:97], v[114:117], v[22:25]
	s_lshl_b32 s2, s2, 6
	v_cvt_pk_f16_f32 v121, v192, v193
	v_cvt_pk_f16_f32 v120, v190, v191
	v_mfma_f32_16x16x32_f16 v[18:21], v[86:89], v[114:117], v[18:21]
	v_cvt_pk_f16_f32 v119, v188, v189
	v_cvt_pk_f16_f32 v118, v186, v187
	s_add_i32 s55, s2, s52
	v_mfma_f32_16x16x32_f16 v[58:61], v[66:69], v[42:45], 0
	v_add_f32_e32 v66, v186, v70
	v_add_f32_e32 v66, v187, v66
	v_add_f32_e32 v66, v188, v66
	v_mfma_f32_16x16x32_f16 v[30:33], v[106:109], v[118:121], v[30:33]
	s_lshr_b32 s84, s55, 5
	s_add_i32 s2, s84, 1
	s_min_i32 s6, s2, s43
	v_mfma_f32_16x16x32_f16 v[26:29], v[98:101], v[118:121], v[26:29]
	s_lshl_b64 s[2:3], s[84:85], 12
	s_ashr_i32 s7, s6, 31
	v_lshl_add_u64 v[136:137], v[138:139], 0, s[2:3]
	v_mfma_f32_16x16x32_f16 v[22:25], v[90:93], v[118:121], v[22:25]
	s_lshl_b64 s[48:49], s[6:7], 12
	v_lshl_add_u64 v[184:185], v[138:139], 0, s[48:49]
	v_cmp_le_i32_e32 vcc, v147, v145
	v_mfma_f32_16x16x32_f16 v[18:21], v[82:85], v[118:121], v[18:21]
	v_cmp_gt_i32_e64 s[6:7], v147, v146
	s_and_b64 s[38:39], vcc, s[6:7]
	v_cmp_lt_i32_e32 vcc, v147, v145
	v_mfma_f32_16x16x32_f16 v[118:121], v[62:65], v[46:49], v[58:61]
	v_cmp_ge_i32_e64 s[6:7], v147, v146
	s_and_b64 s[36:37], vcc, s[6:7]
	v_cmp_le_i32_e32 vcc, v148, v145
	v_add_f32_e32 v58, v189, v66
	v_add_f32_e32 v58, v190, v58
	v_mfma_f32_16x16x32_f16 v[54:57], v[54:57], v[42:45], 0
	v_add_f32_e32 v58, v191, v58
	v_add_f32_e32 v58, v192, v58
	v_add_f32_e32 v58, v193, v58
	v_add_f32_e32 v134, v134, v58
	v_mfma_f32_16x16x32_f16 v[114:117], v[50:53], v[46:49], v[54:57]
	flat_load_dwordx4 v[78:81], v[136:137]
	flat_load_dwordx4 v[74:77], v[136:137] offset:1024
	flat_load_dwordx4 v[66:69], v[184:185]
	flat_load_dwordx4 v[62:65], v[184:185] offset:1024
	flat_load_dwordx4 v[70:73], v[136:137] offset:2048
	flat_load_dwordx4 v[58:61], v[136:137] offset:3072
	flat_load_dwordx4 v[54:57], v[184:185] offset:2048
	flat_load_dwordx4 v[50:53], v[184:185] offset:3072
	v_max_f32_e32 v136, 0xf149f2ca, v126
	v_cndmask_b32_e64 v136, v172, v136, s[38:39]
	v_max_f32_e32 v137, v136, v127
	v_cndmask_b32_e64 v136, v136, v137, s[36:37]
	v_cmp_gt_i32_e64 s[6:7], v148, v146
	v_max_f32_e32 v137, v136, v128
	s_and_b64 s[34:35], vcc, s[6:7]
	v_cndmask_b32_e64 v136, v136, v137, s[34:35]
	v_cmp_le_i32_e32 vcc, v149, v145
	v_cmp_gt_i32_e64 s[6:7], v149, v146
	v_max_f32_e32 v137, v136, v129
	s_and_b64 s[28:29], vcc, s[6:7]
	v_cndmask_b32_e64 v136, v136, v137, s[28:29]
	v_sub_u32_e32 v137, v144, v147
	s_movk_i32 s6, 0x81
	v_cmp_le_i32_e32 vcc, v152, v145
	v_cmp_gt_i32_e64 s[6:7], s6, v137
	v_max_f32_e32 v137, v136, v122
	s_and_b64 s[30:31], vcc, s[6:7]
	v_cndmask_b32_e64 v136, v136, v137, s[30:31]
	v_cmp_le_i32_e32 vcc, v150, v145
	v_cmp_gt_i32_e64 s[6:7], v150, v146
	v_max_f32_e32 v147, v123, v123
	v_max_f32_e32 v137, v136, v147
	s_and_b64 s[26:27], vcc, s[6:7]
	v_cndmask_b32_e64 v136, v136, v137, s[26:27]
	v_cmp_le_i32_e32 vcc, v151, v145
	v_cmp_gt_i32_e64 s[6:7], v151, v146
	v_max_f32_e32 v147, v124, v124
	v_max_f32_e32 v137, v136, v147
	s_and_b64 s[24:25], vcc, s[6:7]
	v_cndmask_b32_e64 v136, v136, v137, s[24:25]
	v_cmp_le_i32_e32 vcc, v153, v145
	v_cmp_gt_i32_e64 s[6:7], v153, v146
	v_max_f32_e32 v147, v125, v125
	v_max_f32_e32 v137, v136, v147
	s_and_b64 s[20:21], vcc, s[6:7]
	v_cndmask_b32_e64 v136, v136, v137, s[20:21]
	v_cmp_le_i32_e32 vcc, v154, v145
	v_cmp_gt_i32_e64 s[6:7], v154, v146
	v_max_f32_e32 v147, v118, v118
	v_max_f32_e32 v137, v136, v147
	s_and_b64 s[22:23], vcc, s[6:7]
	v_cndmask_b32_e64 v136, v136, v137, s[22:23]
	v_cmp_le_i32_e32 vcc, v155, v145
	v_cmp_gt_i32_e64 s[6:7], v155, v146
	v_max_f32_e32 v147, v119, v119
	v_max_f32_e32 v137, v136, v147
	s_and_b64 s[18:19], vcc, s[6:7]
	v_cndmask_b32_e64 v136, v136, v137, s[18:19]
	v_cmp_le_i32_e32 vcc, v156, v145
	v_cmp_gt_i32_e64 s[6:7], v156, v146
	v_max_f32_e32 v147, v120, v120
	v_max_f32_e32 v137, v136, v147
	s_and_b64 s[16:17], vcc, s[6:7]
	v_cndmask_b32_e64 v136, v136, v137, s[16:17]
	v_cmp_le_i32_e32 vcc, v157, v145
	v_cmp_gt_i32_e64 s[6:7], v157, v146
	v_max_f32_e32 v147, v121, v121
	v_max_f32_e32 v137, v136, v147
	s_and_b64 s[12:13], vcc, s[6:7]
	v_cndmask_b32_e64 v136, v136, v137, s[12:13]
	v_cmp_le_i32_e32 vcc, v158, v145
	v_cmp_gt_i32_e64 s[6:7], v158, v146
	v_max_f32_e32 v147, v114, v114
	v_max_f32_e32 v137, v136, v147
	s_and_b64 s[14:15], vcc, s[6:7]
	v_cndmask_b32_e64 v136, v136, v137, s[14:15]
	v_cmp_le_i32_e32 vcc, v159, v145
	v_cmp_gt_i32_e64 s[6:7], v159, v146
	v_max_f32_e32 v147, v115, v115
	v_max_f32_e32 v137, v136, v147
	s_and_b64 s[10:11], vcc, s[6:7]
	v_cndmask_b32_e64 v136, v136, v137, s[10:11]
	v_cmp_le_i32_e32 vcc, v160, v145
	v_cmp_gt_i32_e64 s[6:7], v160, v146
	v_max_f32_e32 v147, v116, v116
	v_max_f32_e32 v137, v136, v147
	s_and_b64 s[8:9], vcc, s[6:7]
	v_cndmask_b32_e64 v136, v136, v137, s[8:9]
	v_cmp_le_i32_e32 vcc, v161, v145
	v_cmp_gt_i32_e64 s[6:7], v161, v146
	v_max_f32_e32 v147, v117, v117
	v_max_f32_e32 v137, v136, v147
	s_and_b64 s[6:7], vcc, s[6:7]
	v_cndmask_b32_e64 v136, v136, v137, s[6:7]
	v_add_f32_e32 v137, 0x41400000, v143
	v_cmp_gt_f32_e32 vcc, v136, v137
	s_cbranch_vccz .LBB0_1028
	v_and_b32_e32 v147, 64, v204
	v_xor_b32_e32 v137, 16, v204
	v_add_u32_e32 v147, 64, v147
	v_cmp_lt_i32_e32 vcc, v137, v147
	s_nop 1
	v_cndmask_b32_e32 v137, v204, v137, vcc
	v_lshlrev_b32_e32 v137, 2, v137
	ds_bpermute_b32 v137, v137, v136
	v_max_f32_e32 v136, v136, v136
	s_waitcnt lgkmcnt(0)
	v_max_f32_e32 v137, v137, v137
	v_max_f32_e32 v136, v136, v137
	v_xor_b32_e32 v137, 32, v204
	v_cmp_lt_i32_e32 vcc, v137, v147
	s_nop 1
	v_cndmask_b32_e32 v137, v204, v137, vcc
	v_lshlrev_b32_e32 v137, 2, v137
	ds_bpermute_b32 v137, v137, v136
	s_waitcnt lgkmcnt(0)
	v_max3_f32 v147, v143, v136, v137
	v_sub_f32_e32 v136, v143, v147
	v_exp_f32_e32 v148, v136
	v_mov_b32_e32 v143, v147
	v_mov_b64_e32 v[136:137], v[142:143]
	v_mul_f32_e32 v135, v135, v148
	v_pk_mul_f32 v[16:17], v[16:17], v[148:149] op_sel_hi:[1,0]
	v_pk_mul_f32 v[14:15], v[14:15], v[148:149] op_sel_hi:[1,0]
	v_pk_mul_f32 v[12:13], v[12:13], v[148:149] op_sel_hi:[1,0]
	v_pk_mul_f32 v[10:11], v[10:11], v[148:149] op_sel_hi:[1,0]
	v_pk_mul_f32 v[8:9], v[8:9], v[148:149] op_sel_hi:[1,0]
	v_pk_mul_f32 v[6:7], v[6:7], v[148:149] op_sel_hi:[1,0]
	v_pk_mul_f32 v[4:5], v[4:5], v[148:149] op_sel_hi:[1,0]
	v_pk_mul_f32 v[2:3], v[2:3], v[148:149] op_sel_hi:[1,0]
	s_branch .LBB0_1029
